# LN rewrite + final LN rewrite + branch-GEMM (Epi3) epilogue gate loads grouped (4 round trips instead of 16-32)
# speedup vs baseline: 1.0165x; 1.0165x over previous
;     __device__ __forceinline__ void operator()(AccMut acc, const pg8::Unit& u, int wr, int wc, int fr, int fq) const {
;         const int n = u.pm >> 5, pm = u.pm & 31, pn = u.pn & 7;
;         const int row0 = pm * 256 + wr * 64 + fr, col0 = pn * 256 + wc * 32 + 8 * fq;
;         const bf16_t* mg = (const bf16_t*)(ws + WS_MG) + n * 2048; bf16_t* mrg = (bf16_t*)(ws + WS_MRG);
; #pragma unroll
;         for (int ai = 0; ai < 2; ++ai)
; #pragma unroll
;             for (int m = 0; m < 4; ++m) { const int row = row0 + ai * 128 + m * 16;
; #pragma unroll
;                 for (int bj = 0; bj < 2; ++bj) { const int col = col0 + bj * 128;
;                     f32x4 g0, g1; unpack_gate(*(const u32x4*)(mg + (size_t)row * 6144 + col), g0, g1);
; #pragma unroll
;                     for (int j = 0; j < 4; ++j) { g0[j] = fmaxf(g0[j], 1e-20f); g1[j] = fmaxf(g1[j], 1e-20f); }
;                     if (n < 2) { f32x4 h0, h1; unpack_gate(*(const u32x4*)(mg + (size_t)row * 6144 + 2048 + col), h0, h1);
; #pragma unroll
;                         for (int j = 0; j < 4; ++j) { g0[j] *= __builtin_amdgcn_rcpf(fmaxf(h0[j], 1e-20f)); g1[j] *= __builtin_amdgcn_rcpf(fmaxf(h1[j], 1e-20f)); }
;                         acc[ai][bj][m][0] *= g0; acc[ai][bj][m][1] *= g1;
.LBB0_1242:
	s_ashr_i32 s9, s2, 5
	s_lshl_b32 s11, s2, 8
	s_and_b32 s11, s11, 0x1f00
	v_add_u32_e32 v2, s11, v160
	s_lshl_b32 s11, s12, 8
	s_and_b32 s11, s11, 0x700
	v_or_b32_e32 v3, s11, v167
	v_lshlrev_b32_e32 v3, 1, v3
	v_mul_u32_u24_e32 v0, 0x3000, v2
	v_add_u32_e32 v0, v0, v3
	v_lshl_add_u32 v2, v2, 12, v3
	s_lshl_b32 s12, s9, 12
	s_add_u32 s22, s44, s12
	s_addc_u32 s23, s45, 0
	s_add_u32 s14, s22, 0x1000
	s_addc_u32 s15, s23, 0
	s_cmp_gt_i32 s9, 1
	s_cbranch_scc1 .Lep3_final
	v_add_u32_e32 v3, 0, v0
	global_load_dwordx4 v[144:147], v3, s[22:23] offset:0
	global_load_dwordx4 v[148:151], v3, s[14:15] offset:0
	global_load_dwordx4 v[152:155], v3, s[22:23] offset:256
	global_load_dwordx4 v[156:159], v3, s[14:15] offset:256
	v_add_u32_e32 v3, 196608, v0
	global_load_dwordx4 v[178:181], v3, s[22:23] offset:0
	global_load_dwordx4 v[182:185], v3, s[14:15] offset:0
	global_load_dwordx4 v[186:189], v3, s[22:23] offset:256
	global_load_dwordx4 v[190:193], v3, s[14:15] offset:256
	s_waitcnt vmcnt(0)
	v_lshlrev_b32_e32 v240, 16, v144
	v_and_b32_e32 v144, 0xffff0000, v144
	v_lshlrev_b32_e32 v241, 16, v148
	v_and_b32_e32 v148, 0xffff0000, v148
	v_max_f32_e32 v240, 0x1e3ce508, v240
	v_max_f32_e32 v144, 0x1e3ce508, v144
	v_max_f32_e32 v241, 0x1e3ce508, v241
	v_max_f32_e32 v148, 0x1e3ce508, v148
	v_rcp_f32_e32 v241, v241
	v_rcp_f32_e32 v148, v148
	v_mul_f32_e32 v240, v240, v241
	v_mul_f32_e32 v144, v144, v148
	v_mul_f32_e32 v128, v128, v240
	v_mul_f32_e32 v129, v129, v144
	v_lshlrev_b32_e32 v240, 16, v145
	v_and_b32_e32 v145, 0xffff0000, v145
	v_lshlrev_b32_e32 v241, 16, v149
	v_and_b32_e32 v149, 0xffff0000, v149
	v_max_f32_e32 v240, 0x1e3ce508, v240
	v_max_f32_e32 v145, 0x1e3ce508, v145
	v_max_f32_e32 v241, 0x1e3ce508, v241
	v_max_f32_e32 v149, 0x1e3ce508, v149
	v_rcp_f32_e32 v241, v241
	v_rcp_f32_e32 v149, v149
	v_mul_f32_e32 v240, v240, v241
	v_mul_f32_e32 v145, v145, v149
	v_mul_f32_e32 v130, v130, v240
	v_mul_f32_e32 v131, v131, v145
	v_lshlrev_b32_e32 v240, 16, v146
	v_and_b32_e32 v146, 0xffff0000, v146
	v_lshlrev_b32_e32 v241, 16, v150
	v_and_b32_e32 v150, 0xffff0000, v150
	v_max_f32_e32 v240, 0x1e3ce508, v240
	v_max_f32_e32 v146, 0x1e3ce508, v146
	v_max_f32_e32 v241, 0x1e3ce508, v241
	v_max_f32_e32 v150, 0x1e3ce508, v150
	v_rcp_f32_e32 v241, v241
	v_rcp_f32_e32 v150, v150
	v_mul_f32_e32 v240, v240, v241
	v_mul_f32_e32 v146, v146, v150
	v_mul_f32_e32 v124, v124, v240
	v_mul_f32_e32 v125, v125, v146
	v_lshlrev_b32_e32 v240, 16, v147
	v_and_b32_e32 v147, 0xffff0000, v147
	v_lshlrev_b32_e32 v241, 16, v151
	v_and_b32_e32 v151, 0xffff0000, v151
	v_max_f32_e32 v240, 0x1e3ce508, v240
	v_max_f32_e32 v147, 0x1e3ce508, v147
	v_max_f32_e32 v241, 0x1e3ce508, v241
	v_max_f32_e32 v151, 0x1e3ce508, v151
	v_rcp_f32_e32 v241, v241
	v_rcp_f32_e32 v151, v151
	v_mul_f32_e32 v240, v240, v241
	v_mul_f32_e32 v147, v147, v151
	v_mul_f32_e32 v126, v126, v240
	v_mul_f32_e32 v127, v127, v147
	v_lshlrev_b32_e32 v240, 16, v152
	v_and_b32_e32 v152, 0xffff0000, v152
	v_lshlrev_b32_e32 v241, 16, v156
	v_and_b32_e32 v156, 0xffff0000, v156
	v_max_f32_e32 v240, 0x1e3ce508, v240
	v_max_f32_e32 v152, 0x1e3ce508, v152
	v_max_f32_e32 v241, 0x1e3ce508, v241
	v_max_f32_e32 v156, 0x1e3ce508, v156
	v_rcp_f32_e32 v241, v241
	v_rcp_f32_e32 v156, v156
	v_mul_f32_e32 v240, v240, v241
	v_mul_f32_e32 v152, v152, v156
	v_mul_f32_e32 v96, v96, v240
	v_mul_f32_e32 v97, v97, v152
	v_lshlrev_b32_e32 v240, 16, v153
	v_and_b32_e32 v153, 0xffff0000, v153
	v_lshlrev_b32_e32 v241, 16, v157
	v_and_b32_e32 v157, 0xffff0000, v157
	v_max_f32_e32 v240, 0x1e3ce508, v240
	v_max_f32_e32 v153, 0x1e3ce508, v153
	v_max_f32_e32 v241, 0x1e3ce508, v241
	v_max_f32_e32 v157, 0x1e3ce508, v157
	v_rcp_f32_e32 v241, v241
	v_rcp_f32_e32 v157, v157
	v_mul_f32_e32 v240, v240, v241
	v_mul_f32_e32 v153, v153, v157
	v_mul_f32_e32 v98, v98, v240
	v_mul_f32_e32 v99, v99, v153
	v_lshlrev_b32_e32 v240, 16, v154
	v_and_b32_e32 v154, 0xffff0000, v154
	v_lshlrev_b32_e32 v241, 16, v158
	v_and_b32_e32 v158, 0xffff0000, v158
	v_max_f32_e32 v240, 0x1e3ce508, v240
	v_max_f32_e32 v154, 0x1e3ce508, v154
	v_max_f32_e32 v241, 0x1e3ce508, v241
	v_max_f32_e32 v158, 0x1e3ce508, v158
	v_rcp_f32_e32 v241, v241
	v_rcp_f32_e32 v158, v158
	v_mul_f32_e32 v240, v240, v241
	v_mul_f32_e32 v154, v154, v158
	v_mul_f32_e32 v92, v92, v240
	v_mul_f32_e32 v93, v93, v154
	v_lshlrev_b32_e32 v240, 16, v155
	v_and_b32_e32 v155, 0xffff0000, v155
	v_lshlrev_b32_e32 v241, 16, v159
	v_and_b32_e32 v159, 0xffff0000, v159
	v_max_f32_e32 v240, 0x1e3ce508, v240
	v_max_f32_e32 v155, 0x1e3ce508, v155
	v_max_f32_e32 v241, 0x1e3ce508, v241
	v_max_f32_e32 v159, 0x1e3ce508, v159
	v_rcp_f32_e32 v241, v241
	v_rcp_f32_e32 v159, v159
	v_mul_f32_e32 v240, v240, v241
	v_mul_f32_e32 v155, v155, v159
	v_mul_f32_e32 v94, v94, v240
	v_mul_f32_e32 v95, v95, v155
	v_lshlrev_b32_e32 v240, 16, v178
	v_and_b32_e32 v178, 0xffff0000, v178
	v_lshlrev_b32_e32 v241, 16, v182
	v_and_b32_e32 v182, 0xffff0000, v182
	v_max_f32_e32 v240, 0x1e3ce508, v240
	v_max_f32_e32 v178, 0x1e3ce508, v178
	v_max_f32_e32 v241, 0x1e3ce508, v241
	v_max_f32_e32 v182, 0x1e3ce508, v182
	v_rcp_f32_e32 v241, v241
	v_rcp_f32_e32 v182, v182
	v_mul_f32_e32 v240, v240, v241
	v_mul_f32_e32 v178, v178, v182
	v_mul_f32_e32 v120, v120, v240
	v_mul_f32_e32 v121, v121, v178
	v_lshlrev_b32_e32 v240, 16, v179
	v_and_b32_e32 v179, 0xffff0000, v179
	v_lshlrev_b32_e32 v241, 16, v183
	v_and_b32_e32 v183, 0xffff0000, v183
	v_max_f32_e32 v240, 0x1e3ce508, v240
	v_max_f32_e32 v179, 0x1e3ce508, v179
	v_max_f32_e32 v241, 0x1e3ce508, v241
	v_max_f32_e32 v183, 0x1e3ce508, v183
	v_rcp_f32_e32 v241, v241
	v_rcp_f32_e32 v183, v183
;     __device__ __forceinline__ void operator()(AccMut acc, const pg8::Unit& u, int wr, int wc, int fr, int fq) const {
;     ...
;             for (int m = 0; m < 4; ++m) { const int row = row0 + ai * 128 + m * 16;
; #pragma unroll
;                 for (int bj = 0; bj < 2; ++bj) { const int col = col0 + bj * 128;
;                     f32x4 g0, g1; unpack_gate(*(const u32x4*)(mg + (size_t)row * 6144 + col), g0, g1);
; #pragma unroll
;                     for (int j = 0; j < 4; ++j) { g0[j] = fmaxf(g0[j], 1e-20f); g1[j] = fmaxf(g1[j], 1e-20f); }
;                     if (n < 2) { f32x4 h0, h1; unpack_gate(*(const u32x4*)(mg + (size_t)row * 6144 + 2048 + col), h0, h1);
; #pragma unroll
;                         for (int j = 0; j < 4; ++j) { g0[j] *= __builtin_amdgcn_rcpf(fmaxf(h0[j], 1e-20f)); g1[j] *= __builtin_amdgcn_rcpf(fmaxf(h1[j], 1e-20f)); }
;                         acc[ai][bj][m][0] *= g0; acc[ai][bj][m][1] *= g1;
	v_mul_f32_e32 v240, v240, v241
	v_mul_f32_e32 v179, v179, v183
	v_mul_f32_e32 v122, v122, v240
	v_mul_f32_e32 v123, v123, v179
	v_lshlrev_b32_e32 v240, 16, v180
	v_and_b32_e32 v180, 0xffff0000, v180
	v_lshlrev_b32_e32 v241, 16, v184
	v_and_b32_e32 v184, 0xffff0000, v184
	v_max_f32_e32 v240, 0x1e3ce508, v240
	v_max_f32_e32 v180, 0x1e3ce508, v180
	v_max_f32_e32 v241, 0x1e3ce508, v241
	v_max_f32_e32 v184, 0x1e3ce508, v184
	v_rcp_f32_e32 v241, v241
	v_rcp_f32_e32 v184, v184
	v_mul_f32_e32 v240, v240, v241
	v_mul_f32_e32 v180, v180, v184
	v_mul_f32_e32 v116, v116, v240
	v_mul_f32_e32 v117, v117, v180
	v_lshlrev_b32_e32 v240, 16, v181
	v_and_b32_e32 v181, 0xffff0000, v181
	v_lshlrev_b32_e32 v241, 16, v185
	v_and_b32_e32 v185, 0xffff0000, v185
	v_max_f32_e32 v240, 0x1e3ce508, v240
	v_max_f32_e32 v181, 0x1e3ce508, v181
	v_max_f32_e32 v241, 0x1e3ce508, v241
	v_max_f32_e32 v185, 0x1e3ce508, v185
	v_rcp_f32_e32 v241, v241
	v_rcp_f32_e32 v185, v185
	v_mul_f32_e32 v240, v240, v241
	v_mul_f32_e32 v181, v181, v185
	v_mul_f32_e32 v118, v118, v240
	v_mul_f32_e32 v119, v119, v181
	v_lshlrev_b32_e32 v240, 16, v186
	v_and_b32_e32 v186, 0xffff0000, v186
	v_lshlrev_b32_e32 v241, 16, v190
	v_and_b32_e32 v190, 0xffff0000, v190
	v_max_f32_e32 v240, 0x1e3ce508, v240
	v_max_f32_e32 v186, 0x1e3ce508, v186
	v_max_f32_e32 v241, 0x1e3ce508, v241
	v_max_f32_e32 v190, 0x1e3ce508, v190
	v_rcp_f32_e32 v241, v241
	v_rcp_f32_e32 v190, v190
	v_mul_f32_e32 v240, v240, v241
	v_mul_f32_e32 v186, v186, v190
	v_mul_f32_e32 v88, v88, v240
	v_mul_f32_e32 v89, v89, v186
	v_lshlrev_b32_e32 v240, 16, v187
	v_and_b32_e32 v187, 0xffff0000, v187
	v_lshlrev_b32_e32 v241, 16, v191
	v_and_b32_e32 v191, 0xffff0000, v191
	v_max_f32_e32 v240, 0x1e3ce508, v240
	v_max_f32_e32 v187, 0x1e3ce508, v187
	v_max_f32_e32 v241, 0x1e3ce508, v241
	v_max_f32_e32 v191, 0x1e3ce508, v191
	v_rcp_f32_e32 v241, v241
	v_rcp_f32_e32 v191, v191
	v_mul_f32_e32 v240, v240, v241
	v_mul_f32_e32 v187, v187, v191
	v_mul_f32_e32 v90, v90, v240
	v_mul_f32_e32 v91, v91, v187
	v_lshlrev_b32_e32 v240, 16, v188
	v_and_b32_e32 v188, 0xffff0000, v188
	v_lshlrev_b32_e32 v241, 16, v192
	v_and_b32_e32 v192, 0xffff0000, v192
	v_max_f32_e32 v240, 0x1e3ce508, v240
	v_max_f32_e32 v188, 0x1e3ce508, v188
	v_max_f32_e32 v241, 0x1e3ce508, v241
	v_max_f32_e32 v192, 0x1e3ce508, v192
	v_rcp_f32_e32 v241, v241
	v_rcp_f32_e32 v192, v192
	v_mul_f32_e32 v240, v240, v241
	v_mul_f32_e32 v188, v188, v192
	v_mul_f32_e32 v84, v84, v240
	v_mul_f32_e32 v85, v85, v188
	v_lshlrev_b32_e32 v240, 16, v189
	v_and_b32_e32 v189, 0xffff0000, v189
	v_lshlrev_b32_e32 v241, 16, v193
	v_and_b32_e32 v193, 0xffff0000, v193
	v_max_f32_e32 v240, 0x1e3ce508, v240
	v_max_f32_e32 v189, 0x1e3ce508, v189
	v_max_f32_e32 v241, 0x1e3ce508, v241
	v_max_f32_e32 v193, 0x1e3ce508, v193
	v_rcp_f32_e32 v241, v241
	v_rcp_f32_e32 v193, v193
	v_mul_f32_e32 v240, v240, v241
	v_mul_f32_e32 v189, v189, v193
	v_mul_f32_e32 v86, v86, v240
	v_mul_f32_e32 v87, v87, v189
	v_add_u32_e32 v3, 393216, v0
	global_load_dwordx4 v[144:147], v3, s[22:23] offset:0
	global_load_dwordx4 v[148:151], v3, s[14:15] offset:0
	global_load_dwordx4 v[152:155], v3, s[22:23] offset:256
	global_load_dwordx4 v[156:159], v3, s[14:15] offset:256
	v_add_u32_e32 v3, 589824, v0
	global_load_dwordx4 v[178:181], v3, s[22:23] offset:0
	global_load_dwordx4 v[182:185], v3, s[14:15] offset:0
	global_load_dwordx4 v[186:189], v3, s[22:23] offset:256
	global_load_dwordx4 v[190:193], v3, s[14:15] offset:256
	s_waitcnt vmcnt(0)
	v_lshlrev_b32_e32 v240, 16, v144
	v_and_b32_e32 v144, 0xffff0000, v144
	v_lshlrev_b32_e32 v241, 16, v148
	v_and_b32_e32 v148, 0xffff0000, v148
	v_max_f32_e32 v240, 0x1e3ce508, v240
	v_max_f32_e32 v144, 0x1e3ce508, v144
	v_max_f32_e32 v241, 0x1e3ce508, v241
	v_max_f32_e32 v148, 0x1e3ce508, v148
	v_rcp_f32_e32 v241, v241
	v_rcp_f32_e32 v148, v148
	v_mul_f32_e32 v240, v240, v241
	v_mul_f32_e32 v144, v144, v148
	v_mul_f32_e32 v112, v112, v240
	v_mul_f32_e32 v113, v113, v144
	v_lshlrev_b32_e32 v240, 16, v145
	v_and_b32_e32 v145, 0xffff0000, v145
	v_lshlrev_b32_e32 v241, 16, v149
	v_and_b32_e32 v149, 0xffff0000, v149
	v_max_f32_e32 v240, 0x1e3ce508, v240
	v_max_f32_e32 v145, 0x1e3ce508, v145
	v_max_f32_e32 v241, 0x1e3ce508, v241
	v_max_f32_e32 v149, 0x1e3ce508, v149
	v_rcp_f32_e32 v241, v241
	v_rcp_f32_e32 v149, v149
	v_mul_f32_e32 v240, v240, v241
	v_mul_f32_e32 v145, v145, v149
	v_mul_f32_e32 v114, v114, v240
	v_mul_f32_e32 v115, v115, v145
	v_lshlrev_b32_e32 v240, 16, v146
	v_and_b32_e32 v146, 0xffff0000, v146
	v_lshlrev_b32_e32 v241, 16, v150
	v_and_b32_e32 v150, 0xffff0000, v150
	v_max_f32_e32 v240, 0x1e3ce508, v240
	v_max_f32_e32 v146, 0x1e3ce508, v146
	v_max_f32_e32 v241, 0x1e3ce508, v241
	v_max_f32_e32 v150, 0x1e3ce508, v150
	v_rcp_f32_e32 v241, v241
	v_rcp_f32_e32 v150, v150
	v_mul_f32_e32 v240, v240, v241
	v_mul_f32_e32 v146, v146, v150
	v_mul_f32_e32 v108, v108, v240
	v_mul_f32_e32 v109, v109, v146
	v_lshlrev_b32_e32 v240, 16, v147
	v_and_b32_e32 v147, 0xffff0000, v147
	v_lshlrev_b32_e32 v241, 16, v151
	v_and_b32_e32 v151, 0xffff0000, v151
	v_max_f32_e32 v240, 0x1e3ce508, v240
	v_max_f32_e32 v147, 0x1e3ce508, v147
	v_max_f32_e32 v241, 0x1e3ce508, v241
	v_max_f32_e32 v151, 0x1e3ce508, v151
	v_rcp_f32_e32 v241, v241
	v_rcp_f32_e32 v151, v151
	v_mul_f32_e32 v240, v240, v241
	v_mul_f32_e32 v147, v147, v151
	v_mul_f32_e32 v110, v110, v240
	v_mul_f32_e32 v111, v111, v147
	v_lshlrev_b32_e32 v240, 16, v152
	v_and_b32_e32 v152, 0xffff0000, v152
	v_lshlrev_b32_e32 v241, 16, v156
	v_and_b32_e32 v156, 0xffff0000, v156
	v_max_f32_e32 v240, 0x1e3ce508, v240
	v_max_f32_e32 v152, 0x1e3ce508, v152
	v_max_f32_e32 v241, 0x1e3ce508, v241
;     __device__ __forceinline__ void operator()(AccMut acc, const pg8::Unit& u, int wr, int wc, int fr, int fq) const {
;     ...
;             for (int m = 0; m < 4; ++m) { const int row = row0 + ai * 128 + m * 16;
; #pragma unroll
;                 for (int bj = 0; bj < 2; ++bj) { const int col = col0 + bj * 128;
;                     f32x4 g0, g1; unpack_gate(*(const u32x4*)(mg + (size_t)row * 6144 + col), g0, g1);
; #pragma unroll
;                     for (int j = 0; j < 4; ++j) { g0[j] = fmaxf(g0[j], 1e-20f); g1[j] = fmaxf(g1[j], 1e-20f); }
;                     if (n < 2) { f32x4 h0, h1; unpack_gate(*(const u32x4*)(mg + (size_t)row * 6144 + 2048 + col), h0, h1);
; #pragma unroll
;                         for (int j = 0; j < 4; ++j) { g0[j] *= __builtin_amdgcn_rcpf(fmaxf(h0[j], 1e-20f)); g1[j] *= __builtin_amdgcn_rcpf(fmaxf(h1[j], 1e-20f)); }
;                         acc[ai][bj][m][0] *= g0; acc[ai][bj][m][1] *= g1;
	v_max_f32_e32 v156, 0x1e3ce508, v156
	v_rcp_f32_e32 v241, v241
	v_rcp_f32_e32 v156, v156
	v_mul_f32_e32 v240, v240, v241
	v_mul_f32_e32 v152, v152, v156
	v_mul_f32_e32 v80, v80, v240
	v_mul_f32_e32 v81, v81, v152
	v_lshlrev_b32_e32 v240, 16, v153
	v_and_b32_e32 v153, 0xffff0000, v153
	v_lshlrev_b32_e32 v241, 16, v157
	v_and_b32_e32 v157, 0xffff0000, v157
	v_max_f32_e32 v240, 0x1e3ce508, v240
	v_max_f32_e32 v153, 0x1e3ce508, v153
	v_max_f32_e32 v241, 0x1e3ce508, v241
	v_max_f32_e32 v157, 0x1e3ce508, v157
	v_rcp_f32_e32 v241, v241
	v_rcp_f32_e32 v157, v157
	v_mul_f32_e32 v240, v240, v241
	v_mul_f32_e32 v153, v153, v157
	v_mul_f32_e32 v82, v82, v240
	v_mul_f32_e32 v83, v83, v153
	v_lshlrev_b32_e32 v240, 16, v154
	v_and_b32_e32 v154, 0xffff0000, v154
	v_lshlrev_b32_e32 v241, 16, v158
	v_and_b32_e32 v158, 0xffff0000, v158
	v_max_f32_e32 v240, 0x1e3ce508, v240
	v_max_f32_e32 v154, 0x1e3ce508, v154
	v_max_f32_e32 v241, 0x1e3ce508, v241
	v_max_f32_e32 v158, 0x1e3ce508, v158
	v_rcp_f32_e32 v241, v241
	v_rcp_f32_e32 v158, v158
	v_mul_f32_e32 v240, v240, v241
	v_mul_f32_e32 v154, v154, v158
	v_mul_f32_e32 v76, v76, v240
	v_mul_f32_e32 v77, v77, v154
	v_lshlrev_b32_e32 v240, 16, v155
	v_and_b32_e32 v155, 0xffff0000, v155
	v_lshlrev_b32_e32 v241, 16, v159
	v_and_b32_e32 v159, 0xffff0000, v159
	v_max_f32_e32 v240, 0x1e3ce508, v240
	v_max_f32_e32 v155, 0x1e3ce508, v155
	v_max_f32_e32 v241, 0x1e3ce508, v241
	v_max_f32_e32 v159, 0x1e3ce508, v159
	v_rcp_f32_e32 v241, v241
	v_rcp_f32_e32 v159, v159
	v_mul_f32_e32 v240, v240, v241
	v_mul_f32_e32 v155, v155, v159
	v_mul_f32_e32 v78, v78, v240
	v_mul_f32_e32 v79, v79, v155
	v_lshlrev_b32_e32 v240, 16, v178
	v_and_b32_e32 v178, 0xffff0000, v178
	v_lshlrev_b32_e32 v241, 16, v182
	v_and_b32_e32 v182, 0xffff0000, v182
	v_max_f32_e32 v240, 0x1e3ce508, v240
	v_max_f32_e32 v178, 0x1e3ce508, v178
	v_max_f32_e32 v241, 0x1e3ce508, v241
	v_max_f32_e32 v182, 0x1e3ce508, v182
	v_rcp_f32_e32 v241, v241
	v_rcp_f32_e32 v182, v182
	v_mul_f32_e32 v240, v240, v241
	v_mul_f32_e32 v178, v178, v182
	v_mul_f32_e32 v104, v104, v240
	v_mul_f32_e32 v105, v105, v178
	v_lshlrev_b32_e32 v240, 16, v179
	v_and_b32_e32 v179, 0xffff0000, v179
	v_lshlrev_b32_e32 v241, 16, v183
	v_and_b32_e32 v183, 0xffff0000, v183
	v_max_f32_e32 v240, 0x1e3ce508, v240
	v_max_f32_e32 v179, 0x1e3ce508, v179
	v_max_f32_e32 v241, 0x1e3ce508, v241
	v_max_f32_e32 v183, 0x1e3ce508, v183
	v_rcp_f32_e32 v241, v241
	v_rcp_f32_e32 v183, v183
	v_mul_f32_e32 v240, v240, v241
	v_mul_f32_e32 v179, v179, v183
	v_mul_f32_e32 v106, v106, v240
	v_mul_f32_e32 v107, v107, v179
	v_lshlrev_b32_e32 v240, 16, v180
	v_and_b32_e32 v180, 0xffff0000, v180
	v_lshlrev_b32_e32 v241, 16, v184
	v_and_b32_e32 v184, 0xffff0000, v184
	v_max_f32_e32 v240, 0x1e3ce508, v240
	v_max_f32_e32 v180, 0x1e3ce508, v180
	v_max_f32_e32 v241, 0x1e3ce508, v241
	v_max_f32_e32 v184, 0x1e3ce508, v184
	v_rcp_f32_e32 v241, v241
	v_rcp_f32_e32 v184, v184
	v_mul_f32_e32 v240, v240, v241
	v_mul_f32_e32 v180, v180, v184
	v_mul_f32_e32 v100, v100, v240
	v_mul_f32_e32 v101, v101, v180
	v_lshlrev_b32_e32 v240, 16, v181
	v_and_b32_e32 v181, 0xffff0000, v181
	v_lshlrev_b32_e32 v241, 16, v185
	v_and_b32_e32 v185, 0xffff0000, v185
	v_max_f32_e32 v240, 0x1e3ce508, v240
	v_max_f32_e32 v181, 0x1e3ce508, v181
	v_max_f32_e32 v241, 0x1e3ce508, v241
	v_max_f32_e32 v185, 0x1e3ce508, v185
	v_rcp_f32_e32 v241, v241
	v_rcp_f32_e32 v185, v185
	v_mul_f32_e32 v240, v240, v241
	v_mul_f32_e32 v181, v181, v185
	v_mul_f32_e32 v102, v102, v240
	v_mul_f32_e32 v103, v103, v181
	v_lshlrev_b32_e32 v240, 16, v186
	v_and_b32_e32 v186, 0xffff0000, v186
	v_lshlrev_b32_e32 v241, 16, v190
	v_and_b32_e32 v190, 0xffff0000, v190
	v_max_f32_e32 v240, 0x1e3ce508, v240
	v_max_f32_e32 v186, 0x1e3ce508, v186
	v_max_f32_e32 v241, 0x1e3ce508, v241
	v_max_f32_e32 v190, 0x1e3ce508, v190
	v_rcp_f32_e32 v241, v241
	v_rcp_f32_e32 v190, v190
	v_mul_f32_e32 v240, v240, v241
	v_mul_f32_e32 v186, v186, v190
	v_mul_f32_e32 v72, v72, v240
	v_mul_f32_e32 v73, v73, v186
	v_lshlrev_b32_e32 v240, 16, v187
	v_and_b32_e32 v187, 0xffff0000, v187
	v_lshlrev_b32_e32 v241, 16, v191
	v_and_b32_e32 v191, 0xffff0000, v191
	v_max_f32_e32 v240, 0x1e3ce508, v240
	v_max_f32_e32 v187, 0x1e3ce508, v187
	v_max_f32_e32 v241, 0x1e3ce508, v241
	v_max_f32_e32 v191, 0x1e3ce508, v191
	v_rcp_f32_e32 v241, v241
	v_rcp_f32_e32 v191, v191
	v_mul_f32_e32 v240, v240, v241
	v_mul_f32_e32 v187, v187, v191
	v_mul_f32_e32 v74, v74, v240
	v_mul_f32_e32 v75, v75, v187
	v_lshlrev_b32_e32 v240, 16, v188
	v_and_b32_e32 v188, 0xffff0000, v188
	v_lshlrev_b32_e32 v241, 16, v192
	v_and_b32_e32 v192, 0xffff0000, v192
	v_max_f32_e32 v240, 0x1e3ce508, v240
	v_max_f32_e32 v188, 0x1e3ce508, v188
	v_max_f32_e32 v241, 0x1e3ce508, v241
	v_max_f32_e32 v192, 0x1e3ce508, v192
	v_rcp_f32_e32 v241, v241
	v_rcp_f32_e32 v192, v192
	v_mul_f32_e32 v240, v240, v241
	v_mul_f32_e32 v188, v188, v192
	v_mul_f32_e32 v68, v68, v240
	v_mul_f32_e32 v69, v69, v188
	v_lshlrev_b32_e32 v240, 16, v189
	v_and_b32_e32 v189, 0xffff0000, v189
	v_lshlrev_b32_e32 v241, 16, v193
	v_and_b32_e32 v193, 0xffff0000, v193
	v_max_f32_e32 v240, 0x1e3ce508, v240
	v_max_f32_e32 v189, 0x1e3ce508, v189
	v_max_f32_e32 v241, 0x1e3ce508, v241
	v_max_f32_e32 v193, 0x1e3ce508, v193
	v_rcp_f32_e32 v241, v241
	v_rcp_f32_e32 v193, v193
	v_mul_f32_e32 v240, v240, v241
	v_mul_f32_e32 v189, v189, v193
	v_mul_f32_e32 v70, v70, v240
	v_mul_f32_e32 v71, v71, v189
	v_add_u32_e32 v3, 1572864, v0
	global_load_dwordx4 v[144:147], v3, s[22:23] offset:0
	global_load_dwordx4 v[148:151], v3, s[14:15] offset:0
	global_load_dwordx4 v[152:155], v3, s[22:23] offset:256
	global_load_dwordx4 v[156:159], v3, s[14:15] offset:256
	v_add_u32_e32 v3, 1769472, v0
	global_load_dwordx4 v[178:181], v3, s[22:23] offset:0
	global_load_dwordx4 v[182:185], v3, s[14:15] offset:0
	global_load_dwordx4 v[186:189], v3, s[22:23] offset:256
	global_load_dwordx4 v[190:193], v3, s[14:15] offset:256
	s_waitcnt vmcnt(0)
;     __device__ __forceinline__ void operator()(AccMut acc, const pg8::Unit& u, int wr, int wc, int fr, int fq) const {
;     ...
;             for (int m = 0; m < 4; ++m) { const int row = row0 + ai * 128 + m * 16;
; #pragma unroll
;                 for (int bj = 0; bj < 2; ++bj) { const int col = col0 + bj * 128;
;                     f32x4 g0, g1; unpack_gate(*(const u32x4*)(mg + (size_t)row * 6144 + col), g0, g1);
; #pragma unroll
;                     for (int j = 0; j < 4; ++j) { g0[j] = fmaxf(g0[j], 1e-20f); g1[j] = fmaxf(g1[j], 1e-20f); }
;                     if (n < 2) { f32x4 h0, h1; unpack_gate(*(const u32x4*)(mg + (size_t)row * 6144 + 2048 + col), h0, h1);
; #pragma unroll
;                         for (int j = 0; j < 4; ++j) { g0[j] *= __builtin_amdgcn_rcpf(fmaxf(h0[j], 1e-20f)); g1[j] *= __builtin_amdgcn_rcpf(fmaxf(h1[j], 1e-20f)); }
;                         acc[ai][bj][m][0] *= g0; acc[ai][bj][m][1] *= g1;
	v_lshlrev_b32_e32 v240, 16, v144
	v_and_b32_e32 v144, 0xffff0000, v144
	v_lshlrev_b32_e32 v241, 16, v148
	v_and_b32_e32 v148, 0xffff0000, v148
	v_max_f32_e32 v240, 0x1e3ce508, v240
	v_max_f32_e32 v144, 0x1e3ce508, v144
	v_max_f32_e32 v241, 0x1e3ce508, v241
	v_max_f32_e32 v148, 0x1e3ce508, v148
	v_rcp_f32_e32 v241, v241
	v_rcp_f32_e32 v148, v148
	v_mul_f32_e32 v240, v240, v241
	v_mul_f32_e32 v144, v144, v148
	v_mul_f32_e32 v64, v64, v240
	v_mul_f32_e32 v65, v65, v144
	v_lshlrev_b32_e32 v240, 16, v145
	v_and_b32_e32 v145, 0xffff0000, v145
	v_lshlrev_b32_e32 v241, 16, v149
	v_and_b32_e32 v149, 0xffff0000, v149
	v_max_f32_e32 v240, 0x1e3ce508, v240
	v_max_f32_e32 v145, 0x1e3ce508, v145
	v_max_f32_e32 v241, 0x1e3ce508, v241
	v_max_f32_e32 v149, 0x1e3ce508, v149
	v_rcp_f32_e32 v241, v241
	v_rcp_f32_e32 v149, v149
	v_mul_f32_e32 v240, v240, v241
	v_mul_f32_e32 v145, v145, v149
	v_mul_f32_e32 v66, v66, v240
	v_mul_f32_e32 v67, v67, v145
	v_lshlrev_b32_e32 v240, 16, v146
	v_and_b32_e32 v146, 0xffff0000, v146
	v_lshlrev_b32_e32 v241, 16, v150
	v_and_b32_e32 v150, 0xffff0000, v150
	v_max_f32_e32 v240, 0x1e3ce508, v240
	v_max_f32_e32 v146, 0x1e3ce508, v146
	v_max_f32_e32 v241, 0x1e3ce508, v241
	v_max_f32_e32 v150, 0x1e3ce508, v150
	v_rcp_f32_e32 v241, v241
	v_rcp_f32_e32 v150, v150
	v_mul_f32_e32 v240, v240, v241
	v_mul_f32_e32 v146, v146, v150
	v_mul_f32_e32 v60, v60, v240
	v_mul_f32_e32 v61, v61, v146
	v_lshlrev_b32_e32 v240, 16, v147
	v_and_b32_e32 v147, 0xffff0000, v147
	v_lshlrev_b32_e32 v241, 16, v151
	v_and_b32_e32 v151, 0xffff0000, v151
	v_max_f32_e32 v240, 0x1e3ce508, v240
	v_max_f32_e32 v147, 0x1e3ce508, v147
	v_max_f32_e32 v241, 0x1e3ce508, v241
	v_max_f32_e32 v151, 0x1e3ce508, v151
	v_rcp_f32_e32 v241, v241
	v_rcp_f32_e32 v151, v151
	v_mul_f32_e32 v240, v240, v241
	v_mul_f32_e32 v147, v147, v151
	v_mul_f32_e32 v62, v62, v240
	v_mul_f32_e32 v63, v63, v147
	v_lshlrev_b32_e32 v240, 16, v152
	v_and_b32_e32 v152, 0xffff0000, v152
	v_lshlrev_b32_e32 v241, 16, v156
	v_and_b32_e32 v156, 0xffff0000, v156
	v_max_f32_e32 v240, 0x1e3ce508, v240
	v_max_f32_e32 v152, 0x1e3ce508, v152
	v_max_f32_e32 v241, 0x1e3ce508, v241
	v_max_f32_e32 v156, 0x1e3ce508, v156
	v_rcp_f32_e32 v241, v241
	v_rcp_f32_e32 v156, v156
	v_mul_f32_e32 v240, v240, v241
	v_mul_f32_e32 v152, v152, v156
	v_mul_f32_e32 v32, v32, v240
	v_mul_f32_e32 v33, v33, v152
	v_lshlrev_b32_e32 v240, 16, v153
	v_and_b32_e32 v153, 0xffff0000, v153
	v_lshlrev_b32_e32 v241, 16, v157
	v_and_b32_e32 v157, 0xffff0000, v157
	v_max_f32_e32 v240, 0x1e3ce508, v240
	v_max_f32_e32 v153, 0x1e3ce508, v153
	v_max_f32_e32 v241, 0x1e3ce508, v241
	v_max_f32_e32 v157, 0x1e3ce508, v157
	v_rcp_f32_e32 v241, v241
	v_rcp_f32_e32 v157, v157
	v_mul_f32_e32 v240, v240, v241
	v_mul_f32_e32 v153, v153, v157
	v_mul_f32_e32 v34, v34, v240
	v_mul_f32_e32 v35, v35, v153
	v_lshlrev_b32_e32 v240, 16, v154
	v_and_b32_e32 v154, 0xffff0000, v154
	v_lshlrev_b32_e32 v241, 16, v158
	v_and_b32_e32 v158, 0xffff0000, v158
	v_max_f32_e32 v240, 0x1e3ce508, v240
	v_max_f32_e32 v154, 0x1e3ce508, v154
	v_max_f32_e32 v241, 0x1e3ce508, v241
	v_max_f32_e32 v158, 0x1e3ce508, v158
	v_rcp_f32_e32 v241, v241
	v_rcp_f32_e32 v158, v158
	v_mul_f32_e32 v240, v240, v241
	v_mul_f32_e32 v154, v154, v158
	v_mul_f32_e32 v28, v28, v240
	v_mul_f32_e32 v29, v29, v154
	v_lshlrev_b32_e32 v240, 16, v155
	v_and_b32_e32 v155, 0xffff0000, v155
	v_lshlrev_b32_e32 v241, 16, v159
	v_and_b32_e32 v159, 0xffff0000, v159
	v_max_f32_e32 v240, 0x1e3ce508, v240
	v_max_f32_e32 v155, 0x1e3ce508, v155
	v_max_f32_e32 v241, 0x1e3ce508, v241
	v_max_f32_e32 v159, 0x1e3ce508, v159
	v_rcp_f32_e32 v241, v241
	v_rcp_f32_e32 v159, v159
	v_mul_f32_e32 v240, v240, v241
	v_mul_f32_e32 v155, v155, v159
	v_mul_f32_e32 v30, v30, v240
	v_mul_f32_e32 v31, v31, v155
	v_lshlrev_b32_e32 v240, 16, v178
	v_and_b32_e32 v178, 0xffff0000, v178
	v_lshlrev_b32_e32 v241, 16, v182
	v_and_b32_e32 v182, 0xffff0000, v182
	v_max_f32_e32 v240, 0x1e3ce508, v240
	v_max_f32_e32 v178, 0x1e3ce508, v178
	v_max_f32_e32 v241, 0x1e3ce508, v241
	v_max_f32_e32 v182, 0x1e3ce508, v182
	v_rcp_f32_e32 v241, v241
	v_rcp_f32_e32 v182, v182
	v_mul_f32_e32 v240, v240, v241
	v_mul_f32_e32 v178, v178, v182
	v_mul_f32_e32 v56, v56, v240
	v_mul_f32_e32 v57, v57, v178
	v_lshlrev_b32_e32 v240, 16, v179
	v_and_b32_e32 v179, 0xffff0000, v179
	v_lshlrev_b32_e32 v241, 16, v183
	v_and_b32_e32 v183, 0xffff0000, v183
	v_max_f32_e32 v240, 0x1e3ce508, v240
	v_max_f32_e32 v179, 0x1e3ce508, v179
	v_max_f32_e32 v241, 0x1e3ce508, v241
	v_max_f32_e32 v183, 0x1e3ce508, v183
	v_rcp_f32_e32 v241, v241
	v_rcp_f32_e32 v183, v183
	v_mul_f32_e32 v240, v240, v241
	v_mul_f32_e32 v179, v179, v183
	v_mul_f32_e32 v58, v58, v240
	v_mul_f32_e32 v59, v59, v179
	v_lshlrev_b32_e32 v240, 16, v180
	v_and_b32_e32 v180, 0xffff0000, v180
	v_lshlrev_b32_e32 v241, 16, v184
	v_and_b32_e32 v184, 0xffff0000, v184
	v_max_f32_e32 v240, 0x1e3ce508, v240
	v_max_f32_e32 v180, 0x1e3ce508, v180
	v_max_f32_e32 v241, 0x1e3ce508, v241
	v_max_f32_e32 v184, 0x1e3ce508, v184
	v_rcp_f32_e32 v241, v241
	v_rcp_f32_e32 v184, v184
	v_mul_f32_e32 v240, v240, v241
	v_mul_f32_e32 v180, v180, v184
	v_mul_f32_e32 v52, v52, v240
	v_mul_f32_e32 v53, v53, v180
	v_lshlrev_b32_e32 v240, 16, v181
	v_and_b32_e32 v181, 0xffff0000, v181
	v_lshlrev_b32_e32 v241, 16, v185
	v_and_b32_e32 v185, 0xffff0000, v185
	v_max_f32_e32 v240, 0x1e3ce508, v240
	v_max_f32_e32 v181, 0x1e3ce508, v181
	v_max_f32_e32 v241, 0x1e3ce508, v241
	v_max_f32_e32 v185, 0x1e3ce508, v185
	v_rcp_f32_e32 v241, v241
	v_rcp_f32_e32 v185, v185
	v_mul_f32_e32 v240, v240, v241
	v_mul_f32_e32 v181, v181, v185
	v_mul_f32_e32 v54, v54, v240
;     __device__ __forceinline__ void operator()(AccMut acc, const pg8::Unit& u, int wr, int wc, int fr, int fq) const {
;     ...
;             for (int m = 0; m < 4; ++m) { const int row = row0 + ai * 128 + m * 16;
; #pragma unroll
;                 for (int bj = 0; bj < 2; ++bj) { const int col = col0 + bj * 128;
;                     f32x4 g0, g1; unpack_gate(*(const u32x4*)(mg + (size_t)row * 6144 + col), g0, g1);
; #pragma unroll
;                     for (int j = 0; j < 4; ++j) { g0[j] = fmaxf(g0[j], 1e-20f); g1[j] = fmaxf(g1[j], 1e-20f); }
;                     if (n < 2) { f32x4 h0, h1; unpack_gate(*(const u32x4*)(mg + (size_t)row * 6144 + 2048 + col), h0, h1);
; #pragma unroll
;                         for (int j = 0; j < 4; ++j) { g0[j] *= __builtin_amdgcn_rcpf(fmaxf(h0[j], 1e-20f)); g1[j] *= __builtin_amdgcn_rcpf(fmaxf(h1[j], 1e-20f)); }
;                         acc[ai][bj][m][0] *= g0; acc[ai][bj][m][1] *= g1;
	v_mul_f32_e32 v55, v55, v181
	v_lshlrev_b32_e32 v240, 16, v186
	v_and_b32_e32 v186, 0xffff0000, v186
	v_lshlrev_b32_e32 v241, 16, v190
	v_and_b32_e32 v190, 0xffff0000, v190
	v_max_f32_e32 v240, 0x1e3ce508, v240
	v_max_f32_e32 v186, 0x1e3ce508, v186
	v_max_f32_e32 v241, 0x1e3ce508, v241
	v_max_f32_e32 v190, 0x1e3ce508, v190
	v_rcp_f32_e32 v241, v241
	v_rcp_f32_e32 v190, v190
	v_mul_f32_e32 v240, v240, v241
	v_mul_f32_e32 v186, v186, v190
	v_mul_f32_e32 v24, v24, v240
	v_mul_f32_e32 v25, v25, v186
	v_lshlrev_b32_e32 v240, 16, v187
	v_and_b32_e32 v187, 0xffff0000, v187
	v_lshlrev_b32_e32 v241, 16, v191
	v_and_b32_e32 v191, 0xffff0000, v191
	v_max_f32_e32 v240, 0x1e3ce508, v240
	v_max_f32_e32 v187, 0x1e3ce508, v187
	v_max_f32_e32 v241, 0x1e3ce508, v241
	v_max_f32_e32 v191, 0x1e3ce508, v191
	v_rcp_f32_e32 v241, v241
	v_rcp_f32_e32 v191, v191
	v_mul_f32_e32 v240, v240, v241
	v_mul_f32_e32 v187, v187, v191
	v_mul_f32_e32 v26, v26, v240
	v_mul_f32_e32 v27, v27, v187
	v_lshlrev_b32_e32 v240, 16, v188
	v_and_b32_e32 v188, 0xffff0000, v188
	v_lshlrev_b32_e32 v241, 16, v192
	v_and_b32_e32 v192, 0xffff0000, v192
	v_max_f32_e32 v240, 0x1e3ce508, v240
	v_max_f32_e32 v188, 0x1e3ce508, v188
	v_max_f32_e32 v241, 0x1e3ce508, v241
	v_max_f32_e32 v192, 0x1e3ce508, v192
	v_rcp_f32_e32 v241, v241
	v_rcp_f32_e32 v192, v192
	v_mul_f32_e32 v240, v240, v241
	v_mul_f32_e32 v188, v188, v192
	v_mul_f32_e32 v20, v20, v240
	v_mul_f32_e32 v21, v21, v188
	v_lshlrev_b32_e32 v240, 16, v189
	v_and_b32_e32 v189, 0xffff0000, v189
	v_lshlrev_b32_e32 v241, 16, v193
	v_and_b32_e32 v193, 0xffff0000, v193
	v_max_f32_e32 v240, 0x1e3ce508, v240
	v_max_f32_e32 v189, 0x1e3ce508, v189
	v_max_f32_e32 v241, 0x1e3ce508, v241
	v_max_f32_e32 v193, 0x1e3ce508, v193
	v_rcp_f32_e32 v241, v241
	v_rcp_f32_e32 v193, v193
	v_mul_f32_e32 v240, v240, v241
	v_mul_f32_e32 v189, v189, v193
	v_mul_f32_e32 v22, v22, v240
	v_mul_f32_e32 v23, v23, v189
	v_add_u32_e32 v3, 1966080, v0
	global_load_dwordx4 v[144:147], v3, s[22:23] offset:0
	global_load_dwordx4 v[148:151], v3, s[14:15] offset:0
	global_load_dwordx4 v[152:155], v3, s[22:23] offset:256
	global_load_dwordx4 v[156:159], v3, s[14:15] offset:256
	v_add_u32_e32 v3, 2162688, v0
	global_load_dwordx4 v[178:181], v3, s[22:23] offset:0
	global_load_dwordx4 v[182:185], v3, s[14:15] offset:0
	global_load_dwordx4 v[186:189], v3, s[22:23] offset:256
	global_load_dwordx4 v[190:193], v3, s[14:15] offset:256
	s_waitcnt vmcnt(0)
	v_lshlrev_b32_e32 v240, 16, v144
	v_and_b32_e32 v144, 0xffff0000, v144
	v_lshlrev_b32_e32 v241, 16, v148
	v_and_b32_e32 v148, 0xffff0000, v148
	v_max_f32_e32 v240, 0x1e3ce508, v240
	v_max_f32_e32 v144, 0x1e3ce508, v144
	v_max_f32_e32 v241, 0x1e3ce508, v241
	v_max_f32_e32 v148, 0x1e3ce508, v148
	v_rcp_f32_e32 v241, v241
	v_rcp_f32_e32 v148, v148
	v_mul_f32_e32 v240, v240, v241
	v_mul_f32_e32 v144, v144, v148
	v_mul_f32_e32 v48, v48, v240
	v_mul_f32_e32 v49, v49, v144
	v_lshlrev_b32_e32 v240, 16, v145
	v_and_b32_e32 v145, 0xffff0000, v145
	v_lshlrev_b32_e32 v241, 16, v149
	v_and_b32_e32 v149, 0xffff0000, v149
	v_max_f32_e32 v240, 0x1e3ce508, v240
	v_max_f32_e32 v145, 0x1e3ce508, v145
	v_max_f32_e32 v241, 0x1e3ce508, v241
	v_max_f32_e32 v149, 0x1e3ce508, v149
	v_rcp_f32_e32 v241, v241
	v_rcp_f32_e32 v149, v149
	v_mul_f32_e32 v240, v240, v241
	v_mul_f32_e32 v145, v145, v149
	v_mul_f32_e32 v50, v50, v240
	v_mul_f32_e32 v51, v51, v145
	v_lshlrev_b32_e32 v240, 16, v146
	v_and_b32_e32 v146, 0xffff0000, v146
	v_lshlrev_b32_e32 v241, 16, v150
	v_and_b32_e32 v150, 0xffff0000, v150
	v_max_f32_e32 v240, 0x1e3ce508, v240
	v_max_f32_e32 v146, 0x1e3ce508, v146
	v_max_f32_e32 v241, 0x1e3ce508, v241
	v_max_f32_e32 v150, 0x1e3ce508, v150
	v_rcp_f32_e32 v241, v241
	v_rcp_f32_e32 v150, v150
	v_mul_f32_e32 v240, v240, v241
	v_mul_f32_e32 v146, v146, v150
	v_mul_f32_e32 v44, v44, v240
	v_mul_f32_e32 v45, v45, v146
	v_lshlrev_b32_e32 v240, 16, v147
	v_and_b32_e32 v147, 0xffff0000, v147
	v_lshlrev_b32_e32 v241, 16, v151
	v_and_b32_e32 v151, 0xffff0000, v151
	v_max_f32_e32 v240, 0x1e3ce508, v240
	v_max_f32_e32 v147, 0x1e3ce508, v147
	v_max_f32_e32 v241, 0x1e3ce508, v241
	v_max_f32_e32 v151, 0x1e3ce508, v151
	v_rcp_f32_e32 v241, v241
	v_rcp_f32_e32 v151, v151
	v_mul_f32_e32 v240, v240, v241
	v_mul_f32_e32 v147, v147, v151
	v_mul_f32_e32 v46, v46, v240
	v_mul_f32_e32 v47, v47, v147
	v_lshlrev_b32_e32 v240, 16, v152
	v_and_b32_e32 v152, 0xffff0000, v152
	v_lshlrev_b32_e32 v241, 16, v156
	v_and_b32_e32 v156, 0xffff0000, v156
	v_max_f32_e32 v240, 0x1e3ce508, v240
	v_max_f32_e32 v152, 0x1e3ce508, v152
	v_max_f32_e32 v241, 0x1e3ce508, v241
	v_max_f32_e32 v156, 0x1e3ce508, v156
	v_rcp_f32_e32 v241, v241
	v_rcp_f32_e32 v156, v156
	v_mul_f32_e32 v240, v240, v241
	v_mul_f32_e32 v152, v152, v156
	v_mul_f32_e32 v16, v16, v240
	v_mul_f32_e32 v17, v17, v152
	v_lshlrev_b32_e32 v240, 16, v153
	v_and_b32_e32 v153, 0xffff0000, v153
	v_lshlrev_b32_e32 v241, 16, v157
	v_and_b32_e32 v157, 0xffff0000, v157
	v_max_f32_e32 v240, 0x1e3ce508, v240
	v_max_f32_e32 v153, 0x1e3ce508, v153
	v_max_f32_e32 v241, 0x1e3ce508, v241
	v_max_f32_e32 v157, 0x1e3ce508, v157
	v_rcp_f32_e32 v241, v241
	v_rcp_f32_e32 v157, v157
	v_mul_f32_e32 v240, v240, v241
	v_mul_f32_e32 v153, v153, v157
	v_mul_f32_e32 v18, v18, v240
	v_mul_f32_e32 v19, v19, v153
	v_lshlrev_b32_e32 v240, 16, v154
	v_and_b32_e32 v154, 0xffff0000, v154
	v_lshlrev_b32_e32 v241, 16, v158
	v_and_b32_e32 v158, 0xffff0000, v158
	v_max_f32_e32 v240, 0x1e3ce508, v240
	v_max_f32_e32 v154, 0x1e3ce508, v154
	v_max_f32_e32 v241, 0x1e3ce508, v241
	v_max_f32_e32 v158, 0x1e3ce508, v158
	v_rcp_f32_e32 v241, v241
	v_rcp_f32_e32 v158, v158
;     __device__ __forceinline__ void operator()(AccMut acc, const pg8::Unit& u, int wr, int wc, int fr, int fq) const {
;     ...
;             for (int m = 0; m < 4; ++m) { const int row = row0 + ai * 128 + m * 16;
; #pragma unroll
;                 for (int bj = 0; bj < 2; ++bj) { const int col = col0 + bj * 128;
;                     f32x4 g0, g1; unpack_gate(*(const u32x4*)(mg + (size_t)row * 6144 + col), g0, g1);
; #pragma unroll
;                     for (int j = 0; j < 4; ++j) { g0[j] = fmaxf(g0[j], 1e-20f); g1[j] = fmaxf(g1[j], 1e-20f); }
;                     if (n < 2) { f32x4 h0, h1; unpack_gate(*(const u32x4*)(mg + (size_t)row * 6144 + 2048 + col), h0, h1);
; #pragma unroll
;                         for (int j = 0; j < 4; ++j) { g0[j] *= __builtin_amdgcn_rcpf(fmaxf(h0[j], 1e-20f)); g1[j] *= __builtin_amdgcn_rcpf(fmaxf(h1[j], 1e-20f)); }
;                         acc[ai][bj][m][0] *= g0; acc[ai][bj][m][1] *= g1;
	v_mul_f32_e32 v240, v240, v241
	v_mul_f32_e32 v154, v154, v158
	v_mul_f32_e32 v12, v12, v240
	v_mul_f32_e32 v13, v13, v154
	v_lshlrev_b32_e32 v240, 16, v155
	v_and_b32_e32 v155, 0xffff0000, v155
	v_lshlrev_b32_e32 v241, 16, v159
	v_and_b32_e32 v159, 0xffff0000, v159
	v_max_f32_e32 v240, 0x1e3ce508, v240
	v_max_f32_e32 v155, 0x1e3ce508, v155
	v_max_f32_e32 v241, 0x1e3ce508, v241
	v_max_f32_e32 v159, 0x1e3ce508, v159
	v_rcp_f32_e32 v241, v241
	v_rcp_f32_e32 v159, v159
	v_mul_f32_e32 v240, v240, v241
	v_mul_f32_e32 v155, v155, v159
	v_mul_f32_e32 v14, v14, v240
	v_mul_f32_e32 v15, v15, v155
	v_lshlrev_b32_e32 v240, 16, v178
	v_and_b32_e32 v178, 0xffff0000, v178
	v_lshlrev_b32_e32 v241, 16, v182
	v_and_b32_e32 v182, 0xffff0000, v182
	v_max_f32_e32 v240, 0x1e3ce508, v240
	v_max_f32_e32 v178, 0x1e3ce508, v178
	v_max_f32_e32 v241, 0x1e3ce508, v241
	v_max_f32_e32 v182, 0x1e3ce508, v182
	v_rcp_f32_e32 v241, v241
	v_rcp_f32_e32 v182, v182
	v_mul_f32_e32 v240, v240, v241
	v_mul_f32_e32 v178, v178, v182
	v_mul_f32_e32 v40, v40, v240
	v_mul_f32_e32 v41, v41, v178
	v_lshlrev_b32_e32 v240, 16, v179
	v_and_b32_e32 v179, 0xffff0000, v179
	v_lshlrev_b32_e32 v241, 16, v183
	v_and_b32_e32 v183, 0xffff0000, v183
	v_max_f32_e32 v240, 0x1e3ce508, v240
	v_max_f32_e32 v179, 0x1e3ce508, v179
	v_max_f32_e32 v241, 0x1e3ce508, v241
	v_max_f32_e32 v183, 0x1e3ce508, v183
	v_rcp_f32_e32 v241, v241
	v_rcp_f32_e32 v183, v183
	v_mul_f32_e32 v240, v240, v241
	v_mul_f32_e32 v179, v179, v183
	v_mul_f32_e32 v42, v42, v240
	v_mul_f32_e32 v43, v43, v179
	v_lshlrev_b32_e32 v240, 16, v180
	v_and_b32_e32 v180, 0xffff0000, v180
	v_lshlrev_b32_e32 v241, 16, v184
	v_and_b32_e32 v184, 0xffff0000, v184
	v_max_f32_e32 v240, 0x1e3ce508, v240
	v_max_f32_e32 v180, 0x1e3ce508, v180
	v_max_f32_e32 v241, 0x1e3ce508, v241
	v_max_f32_e32 v184, 0x1e3ce508, v184
	v_rcp_f32_e32 v241, v241
	v_rcp_f32_e32 v184, v184
	v_mul_f32_e32 v240, v240, v241
	v_mul_f32_e32 v180, v180, v184
	v_mul_f32_e32 v36, v36, v240
	v_mul_f32_e32 v37, v37, v180
	v_lshlrev_b32_e32 v240, 16, v181
	v_and_b32_e32 v181, 0xffff0000, v181
	v_lshlrev_b32_e32 v241, 16, v185
	v_and_b32_e32 v185, 0xffff0000, v185
	v_max_f32_e32 v240, 0x1e3ce508, v240
	v_max_f32_e32 v181, 0x1e3ce508, v181
	v_max_f32_e32 v241, 0x1e3ce508, v241
	v_max_f32_e32 v185, 0x1e3ce508, v185
	v_rcp_f32_e32 v241, v241
	v_rcp_f32_e32 v185, v185
	v_mul_f32_e32 v240, v240, v241
	v_mul_f32_e32 v181, v181, v185
	v_mul_f32_e32 v38, v38, v240
	v_mul_f32_e32 v39, v39, v181
	v_lshlrev_b32_e32 v240, 16, v186
	v_and_b32_e32 v186, 0xffff0000, v186
	v_lshlrev_b32_e32 v241, 16, v190
	v_and_b32_e32 v190, 0xffff0000, v190
	v_max_f32_e32 v240, 0x1e3ce508, v240
	v_max_f32_e32 v186, 0x1e3ce508, v186
	v_max_f32_e32 v241, 0x1e3ce508, v241
	v_max_f32_e32 v190, 0x1e3ce508, v190
	v_rcp_f32_e32 v241, v241
	v_rcp_f32_e32 v190, v190
	v_mul_f32_e32 v240, v240, v241
	v_mul_f32_e32 v186, v186, v190
	v_mul_f32_e32 v8, v8, v240
	v_mul_f32_e32 v9, v9, v186
	v_lshlrev_b32_e32 v240, 16, v187
	v_and_b32_e32 v187, 0xffff0000, v187
	v_lshlrev_b32_e32 v241, 16, v191
	v_and_b32_e32 v191, 0xffff0000, v191
	v_max_f32_e32 v240, 0x1e3ce508, v240
	v_max_f32_e32 v187, 0x1e3ce508, v187
	v_max_f32_e32 v241, 0x1e3ce508, v241
	v_max_f32_e32 v191, 0x1e3ce508, v191
	v_rcp_f32_e32 v241, v241
	v_rcp_f32_e32 v191, v191
	v_mul_f32_e32 v240, v240, v241
	v_mul_f32_e32 v187, v187, v191
	v_mul_f32_e32 v10, v10, v240
	v_mul_f32_e32 v11, v11, v187
	v_lshlrev_b32_e32 v240, 16, v188
	v_and_b32_e32 v188, 0xffff0000, v188
	v_lshlrev_b32_e32 v241, 16, v192
	v_and_b32_e32 v192, 0xffff0000, v192
	v_max_f32_e32 v240, 0x1e3ce508, v240
	v_max_f32_e32 v188, 0x1e3ce508, v188
	v_max_f32_e32 v241, 0x1e3ce508, v241
	v_max_f32_e32 v192, 0x1e3ce508, v192
	v_rcp_f32_e32 v241, v241
	v_rcp_f32_e32 v192, v192
	v_mul_f32_e32 v240, v240, v241
	v_mul_f32_e32 v188, v188, v192
	v_mul_f32_e32 v4, v4, v240
	v_mul_f32_e32 v5, v5, v188
	v_lshlrev_b32_e32 v240, 16, v189
	v_and_b32_e32 v189, 0xffff0000, v189
	v_lshlrev_b32_e32 v241, 16, v193
	v_and_b32_e32 v193, 0xffff0000, v193
	v_max_f32_e32 v240, 0x1e3ce508, v240
	v_max_f32_e32 v189, 0x1e3ce508, v189
	v_max_f32_e32 v241, 0x1e3ce508, v241
	v_max_f32_e32 v193, 0x1e3ce508, v193
	v_rcp_f32_e32 v241, v241
	v_rcp_f32_e32 v193, v193
	v_mul_f32_e32 v240, v240, v241
	v_mul_f32_e32 v189, v189, v193
	v_mul_f32_e32 v6, v6, v240
	v_mul_f32_e32 v7, v7, v189
	s_branch .Lep3_done
; __device__ __forceinline__ unsigned pk2(float lo, float hi) { f32x2 v = {lo, hi}; bf16x2_t b = __builtin_convertvector(v, bf16x2_t); return __builtin_bit_cast(unsigned, b); }
;     __device__ __forceinline__ void operator()(AccMut acc, const pg8::Unit& u, int wr, int wc, int fr, int fq) const {
;     ...
;                 for (int bj = 0; bj < 2; ++bj) { const int col = col0 + bj * 128;
;                     f32x4 g0, g1; unpack_gate(*(const u32x4*)(mg + (size_t)row * 6144 + col), g0, g1);
; #pragma unroll
;                     for (int j = 0; j < 4; ++j) { g0[j] = fmaxf(g0[j], 1e-20f); g1[j] = fmaxf(g1[j], 1e-20f); }
;                     if (n < 2) { f32x4 h0, h1; unpack_gate(*(const u32x4*)(mg + (size_t)row * 6144 + 2048 + col), h0, h1);
; #pragma unroll
;                         for (int j = 0; j < 4; ++j) { g0[j] *= __builtin_amdgcn_rcpf(fmaxf(h0[j], 1e-20f)); g1[j] *= __builtin_amdgcn_rcpf(fmaxf(h1[j], 1e-20f)); }
;                         acc[ai][bj][m][0] *= g0; acc[ai][bj][m][1] *= g1;
;                     } else {
;                         const f32x4 v0 = acc[ai][bj][m][0] * g0, v1 = acc[ai][bj][m][1] * g1;
;                         u32x4 w; w.x = pk2(v0[0], v0[1]); w.y = pk2(v0[2], v0[3]); w.z = pk2(v1[0], v1[1]); w.w = pk2(v1[2], v1[3]); *(u32x4*)(mrg + (size_t)row * 2048 + col) = w; } } }
.Lep3_final:
	v_add_u32_e32 v3, 0, v0
	global_load_dwordx4 v[144:147], v3, s[22:23] offset:0
	global_load_dwordx4 v[148:151], v3, s[22:23] offset:256
	v_add_u32_e32 v3, 196608, v0
	global_load_dwordx4 v[152:155], v3, s[22:23] offset:0
	global_load_dwordx4 v[156:159], v3, s[22:23] offset:256
	s_waitcnt vmcnt(0)
	v_add_u32_e32 v3, 0, v2
	v_lshlrev_b32_e32 v242, 16, v144
	v_and_b32_e32 v144, 0xffff0000, v144
	v_max_f32_e32 v242, 0x1e3ce508, v242
	v_max_f32_e32 v144, 0x1e3ce508, v144
	v_mul_f32_e32 v242, v128, v242
	v_mul_f32_e32 v144, v129, v144
	v_cvt_pk_bf16_f32 v178, v242, v144
	v_lshlrev_b32_e32 v242, 16, v145
	v_and_b32_e32 v145, 0xffff0000, v145
	v_max_f32_e32 v242, 0x1e3ce508, v242
	v_max_f32_e32 v145, 0x1e3ce508, v145
	v_mul_f32_e32 v242, v130, v242
	v_mul_f32_e32 v145, v131, v145
	v_cvt_pk_bf16_f32 v179, v242, v145
	v_lshlrev_b32_e32 v242, 16, v146
	v_and_b32_e32 v146, 0xffff0000, v146
	v_max_f32_e32 v242, 0x1e3ce508, v242
	v_max_f32_e32 v146, 0x1e3ce508, v146
	v_mul_f32_e32 v242, v124, v242
	v_mul_f32_e32 v146, v125, v146
	v_cvt_pk_bf16_f32 v180, v242, v146
	v_lshlrev_b32_e32 v242, 16, v147
	v_and_b32_e32 v147, 0xffff0000, v147
	v_max_f32_e32 v242, 0x1e3ce508, v242
	v_max_f32_e32 v147, 0x1e3ce508, v147
	v_mul_f32_e32 v242, v126, v242
	v_mul_f32_e32 v147, v127, v147
	v_cvt_pk_bf16_f32 v181, v242, v147
	global_store_dwordx4 v3, v[178:181], s[6:7] offset:0
	v_lshlrev_b32_e32 v242, 16, v148
	v_and_b32_e32 v148, 0xffff0000, v148
	v_max_f32_e32 v242, 0x1e3ce508, v242
	v_max_f32_e32 v148, 0x1e3ce508, v148
	v_mul_f32_e32 v242, v96, v242
	v_mul_f32_e32 v148, v97, v148
	v_cvt_pk_bf16_f32 v182, v242, v148
	v_lshlrev_b32_e32 v242, 16, v149
	v_and_b32_e32 v149, 0xffff0000, v149
	v_max_f32_e32 v242, 0x1e3ce508, v242
	v_max_f32_e32 v149, 0x1e3ce508, v149
	v_mul_f32_e32 v242, v98, v242
	v_mul_f32_e32 v149, v99, v149
	v_cvt_pk_bf16_f32 v183, v242, v149
	v_lshlrev_b32_e32 v242, 16, v150
	v_and_b32_e32 v150, 0xffff0000, v150
	v_max_f32_e32 v242, 0x1e3ce508, v242
	v_max_f32_e32 v150, 0x1e3ce508, v150
	v_mul_f32_e32 v242, v92, v242
	v_mul_f32_e32 v150, v93, v150
	v_cvt_pk_bf16_f32 v184, v242, v150
	v_lshlrev_b32_e32 v242, 16, v151
	v_and_b32_e32 v151, 0xffff0000, v151
	v_max_f32_e32 v242, 0x1e3ce508, v242
	v_max_f32_e32 v151, 0x1e3ce508, v151
	v_mul_f32_e32 v242, v94, v242
	v_mul_f32_e32 v151, v95, v151
	v_cvt_pk_bf16_f32 v185, v242, v151
	global_store_dwordx4 v3, v[182:185], s[6:7] offset:256
	v_add_u32_e32 v3, 65536, v2
	v_lshlrev_b32_e32 v242, 16, v152
	v_and_b32_e32 v152, 0xffff0000, v152
	v_max_f32_e32 v242, 0x1e3ce508, v242
	v_max_f32_e32 v152, 0x1e3ce508, v152
	v_mul_f32_e32 v242, v120, v242
	v_mul_f32_e32 v152, v121, v152
	v_cvt_pk_bf16_f32 v186, v242, v152
	v_lshlrev_b32_e32 v242, 16, v153
	v_and_b32_e32 v153, 0xffff0000, v153
	v_max_f32_e32 v242, 0x1e3ce508, v242
	v_max_f32_e32 v153, 0x1e3ce508, v153
	v_mul_f32_e32 v242, v122, v242
	v_mul_f32_e32 v153, v123, v153
	v_cvt_pk_bf16_f32 v187, v242, v153
	v_lshlrev_b32_e32 v242, 16, v154
	v_and_b32_e32 v154, 0xffff0000, v154
	v_max_f32_e32 v242, 0x1e3ce508, v242
	v_max_f32_e32 v154, 0x1e3ce508, v154
	v_mul_f32_e32 v242, v116, v242
	v_mul_f32_e32 v154, v117, v154
	v_cvt_pk_bf16_f32 v188, v242, v154
	v_lshlrev_b32_e32 v242, 16, v155
	v_and_b32_e32 v155, 0xffff0000, v155
	v_max_f32_e32 v242, 0x1e3ce508, v242
	v_max_f32_e32 v155, 0x1e3ce508, v155
	v_mul_f32_e32 v242, v118, v242
	v_mul_f32_e32 v155, v119, v155
	v_cvt_pk_bf16_f32 v189, v242, v155
	global_store_dwordx4 v3, v[186:189], s[6:7] offset:0
	v_lshlrev_b32_e32 v242, 16, v156
	v_and_b32_e32 v156, 0xffff0000, v156
	v_max_f32_e32 v242, 0x1e3ce508, v242
	v_max_f32_e32 v156, 0x1e3ce508, v156
	v_mul_f32_e32 v242, v88, v242
	v_mul_f32_e32 v156, v89, v156
	v_cvt_pk_bf16_f32 v190, v242, v156
	v_lshlrev_b32_e32 v242, 16, v157
	v_and_b32_e32 v157, 0xffff0000, v157
	v_max_f32_e32 v242, 0x1e3ce508, v242
	v_max_f32_e32 v157, 0x1e3ce508, v157
	v_mul_f32_e32 v242, v90, v242
	v_mul_f32_e32 v157, v91, v157
	v_cvt_pk_bf16_f32 v191, v242, v157
	v_lshlrev_b32_e32 v242, 16, v158
	v_and_b32_e32 v158, 0xffff0000, v158
	v_max_f32_e32 v242, 0x1e3ce508, v242
	v_max_f32_e32 v158, 0x1e3ce508, v158
	v_mul_f32_e32 v242, v84, v242
	v_mul_f32_e32 v158, v85, v158
	v_cvt_pk_bf16_f32 v192, v242, v158
	v_lshlrev_b32_e32 v242, 16, v159
	v_and_b32_e32 v159, 0xffff0000, v159
	v_max_f32_e32 v242, 0x1e3ce508, v242
	v_max_f32_e32 v159, 0x1e3ce508, v159
	v_mul_f32_e32 v242, v86, v242
	v_mul_f32_e32 v159, v87, v159
	v_cvt_pk_bf16_f32 v193, v242, v159
	global_store_dwordx4 v3, v[190:193], s[6:7] offset:256
	v_add_u32_e32 v3, 393216, v0
	global_load_dwordx4 v[144:147], v3, s[22:23] offset:0
	global_load_dwordx4 v[148:151], v3, s[22:23] offset:256
	v_add_u32_e32 v3, 589824, v0
	global_load_dwordx4 v[152:155], v3, s[22:23] offset:0
	global_load_dwordx4 v[156:159], v3, s[22:23] offset:256
	s_waitcnt vmcnt(0)
; __device__ __forceinline__ unsigned pk2(float lo, float hi) { f32x2 v = {lo, hi}; bf16x2_t b = __builtin_convertvector(v, bf16x2_t); return __builtin_bit_cast(unsigned, b); }
;     __device__ __forceinline__ void operator()(AccMut acc, const pg8::Unit& u, int wr, int wc, int fr, int fq) const {
;     ...
;                 for (int bj = 0; bj < 2; ++bj) { const int col = col0 + bj * 128;
;                     f32x4 g0, g1; unpack_gate(*(const u32x4*)(mg + (size_t)row * 6144 + col), g0, g1);
; #pragma unroll
;                     for (int j = 0; j < 4; ++j) { g0[j] = fmaxf(g0[j], 1e-20f); g1[j] = fmaxf(g1[j], 1e-20f); }
;                     if (n < 2) { f32x4 h0, h1; unpack_gate(*(const u32x4*)(mg + (size_t)row * 6144 + 2048 + col), h0, h1);
; #pragma unroll
;                         for (int j = 0; j < 4; ++j) { g0[j] *= __builtin_amdgcn_rcpf(fmaxf(h0[j], 1e-20f)); g1[j] *= __builtin_amdgcn_rcpf(fmaxf(h1[j], 1e-20f)); }
;                         acc[ai][bj][m][0] *= g0; acc[ai][bj][m][1] *= g1;
;                     } else {
;                         const f32x4 v0 = acc[ai][bj][m][0] * g0, v1 = acc[ai][bj][m][1] * g1;
;                         u32x4 w; w.x = pk2(v0[0], v0[1]); w.y = pk2(v0[2], v0[3]); w.z = pk2(v1[0], v1[1]); w.w = pk2(v1[2], v1[3]); *(u32x4*)(mrg + (size_t)row * 2048 + col) = w; } } }
	v_add_u32_e32 v3, 131072, v2
	v_lshlrev_b32_e32 v242, 16, v144
	v_and_b32_e32 v144, 0xffff0000, v144
	v_max_f32_e32 v242, 0x1e3ce508, v242
	v_max_f32_e32 v144, 0x1e3ce508, v144
	v_mul_f32_e32 v242, v112, v242
	v_mul_f32_e32 v144, v113, v144
	v_cvt_pk_bf16_f32 v194, v242, v144
	v_lshlrev_b32_e32 v242, 16, v145
	v_and_b32_e32 v145, 0xffff0000, v145
	v_max_f32_e32 v242, 0x1e3ce508, v242
	v_max_f32_e32 v145, 0x1e3ce508, v145
	v_mul_f32_e32 v242, v114, v242
	v_mul_f32_e32 v145, v115, v145
	v_cvt_pk_bf16_f32 v195, v242, v145
	v_lshlrev_b32_e32 v242, 16, v146
	v_and_b32_e32 v146, 0xffff0000, v146
	v_max_f32_e32 v242, 0x1e3ce508, v242
	v_max_f32_e32 v146, 0x1e3ce508, v146
	v_mul_f32_e32 v242, v108, v242
	v_mul_f32_e32 v146, v109, v146
	v_cvt_pk_bf16_f32 v196, v242, v146
	v_lshlrev_b32_e32 v242, 16, v147
	v_and_b32_e32 v147, 0xffff0000, v147
	v_max_f32_e32 v242, 0x1e3ce508, v242
	v_max_f32_e32 v147, 0x1e3ce508, v147
	v_mul_f32_e32 v242, v110, v242
	v_mul_f32_e32 v147, v111, v147
	v_cvt_pk_bf16_f32 v197, v242, v147
	global_store_dwordx4 v3, v[194:197], s[6:7] offset:0
	v_lshlrev_b32_e32 v242, 16, v148
	v_and_b32_e32 v148, 0xffff0000, v148
	v_max_f32_e32 v242, 0x1e3ce508, v242
	v_max_f32_e32 v148, 0x1e3ce508, v148
	v_mul_f32_e32 v242, v80, v242
	v_mul_f32_e32 v148, v81, v148
	v_cvt_pk_bf16_f32 v198, v242, v148
	v_lshlrev_b32_e32 v242, 16, v149
	v_and_b32_e32 v149, 0xffff0000, v149
	v_max_f32_e32 v242, 0x1e3ce508, v242
	v_max_f32_e32 v149, 0x1e3ce508, v149
	v_mul_f32_e32 v242, v82, v242
	v_mul_f32_e32 v149, v83, v149
	v_cvt_pk_bf16_f32 v199, v242, v149
	v_lshlrev_b32_e32 v242, 16, v150
	v_and_b32_e32 v150, 0xffff0000, v150
	v_max_f32_e32 v242, 0x1e3ce508, v242
	v_max_f32_e32 v150, 0x1e3ce508, v150
	v_mul_f32_e32 v242, v76, v242
	v_mul_f32_e32 v150, v77, v150
	v_cvt_pk_bf16_f32 v200, v242, v150
	v_lshlrev_b32_e32 v242, 16, v151
	v_and_b32_e32 v151, 0xffff0000, v151
	v_max_f32_e32 v242, 0x1e3ce508, v242
	v_max_f32_e32 v151, 0x1e3ce508, v151
	v_mul_f32_e32 v242, v78, v242
	v_mul_f32_e32 v151, v79, v151
	v_cvt_pk_bf16_f32 v201, v242, v151
	global_store_dwordx4 v3, v[198:201], s[6:7] offset:256
	v_add_u32_e32 v3, 196608, v2
	v_lshlrev_b32_e32 v242, 16, v152
	v_and_b32_e32 v152, 0xffff0000, v152
	v_max_f32_e32 v242, 0x1e3ce508, v242
	v_max_f32_e32 v152, 0x1e3ce508, v152
	v_mul_f32_e32 v242, v104, v242
	v_mul_f32_e32 v152, v105, v152
	v_cvt_pk_bf16_f32 v202, v242, v152
	v_lshlrev_b32_e32 v242, 16, v153
	v_and_b32_e32 v153, 0xffff0000, v153
	v_max_f32_e32 v242, 0x1e3ce508, v242
	v_max_f32_e32 v153, 0x1e3ce508, v153
	v_mul_f32_e32 v242, v106, v242
	v_mul_f32_e32 v153, v107, v153
	v_cvt_pk_bf16_f32 v203, v242, v153
	v_lshlrev_b32_e32 v242, 16, v154
	v_and_b32_e32 v154, 0xffff0000, v154
	v_max_f32_e32 v242, 0x1e3ce508, v242
	v_max_f32_e32 v154, 0x1e3ce508, v154
	v_mul_f32_e32 v242, v100, v242
	v_mul_f32_e32 v154, v101, v154
	v_cvt_pk_bf16_f32 v204, v242, v154
	v_lshlrev_b32_e32 v242, 16, v155
	v_and_b32_e32 v155, 0xffff0000, v155
	v_max_f32_e32 v242, 0x1e3ce508, v242
	v_max_f32_e32 v155, 0x1e3ce508, v155
	v_mul_f32_e32 v242, v102, v242
	v_mul_f32_e32 v155, v103, v155
	v_cvt_pk_bf16_f32 v205, v242, v155
	global_store_dwordx4 v3, v[202:205], s[6:7] offset:0
	v_lshlrev_b32_e32 v242, 16, v156
	v_and_b32_e32 v156, 0xffff0000, v156
	v_max_f32_e32 v242, 0x1e3ce508, v242
	v_max_f32_e32 v156, 0x1e3ce508, v156
	v_mul_f32_e32 v242, v72, v242
	v_mul_f32_e32 v156, v73, v156
	v_cvt_pk_bf16_f32 v224, v242, v156
	v_lshlrev_b32_e32 v242, 16, v157
	v_and_b32_e32 v157, 0xffff0000, v157
	v_max_f32_e32 v242, 0x1e3ce508, v242
	v_max_f32_e32 v157, 0x1e3ce508, v157
	v_mul_f32_e32 v242, v74, v242
	v_mul_f32_e32 v157, v75, v157
	v_cvt_pk_bf16_f32 v225, v242, v157
	v_lshlrev_b32_e32 v242, 16, v158
	v_and_b32_e32 v158, 0xffff0000, v158
	v_max_f32_e32 v242, 0x1e3ce508, v242
	v_max_f32_e32 v158, 0x1e3ce508, v158
	v_mul_f32_e32 v242, v68, v242
	v_mul_f32_e32 v158, v69, v158
	v_cvt_pk_bf16_f32 v226, v242, v158
	v_lshlrev_b32_e32 v242, 16, v159
	v_and_b32_e32 v159, 0xffff0000, v159
	v_max_f32_e32 v242, 0x1e3ce508, v242
	v_max_f32_e32 v159, 0x1e3ce508, v159
	v_mul_f32_e32 v242, v70, v242
	v_mul_f32_e32 v159, v71, v159
	v_cvt_pk_bf16_f32 v227, v242, v159
	global_store_dwordx4 v3, v[224:227], s[6:7] offset:256
	v_add_u32_e32 v3, 1572864, v0
	global_load_dwordx4 v[144:147], v3, s[22:23] offset:0
	global_load_dwordx4 v[148:151], v3, s[22:23] offset:256
	v_add_u32_e32 v3, 1769472, v0
	global_load_dwordx4 v[152:155], v3, s[22:23] offset:0
	global_load_dwordx4 v[156:159], v3, s[22:23] offset:256
	s_waitcnt vmcnt(0)
; __device__ __forceinline__ unsigned pk2(float lo, float hi) { f32x2 v = {lo, hi}; bf16x2_t b = __builtin_convertvector(v, bf16x2_t); return __builtin_bit_cast(unsigned, b); }
;     __device__ __forceinline__ void operator()(AccMut acc, const pg8::Unit& u, int wr, int wc, int fr, int fq) const {
;     ...
;                 for (int bj = 0; bj < 2; ++bj) { const int col = col0 + bj * 128;
;                     f32x4 g0, g1; unpack_gate(*(const u32x4*)(mg + (size_t)row * 6144 + col), g0, g1);
; #pragma unroll
;                     for (int j = 0; j < 4; ++j) { g0[j] = fmaxf(g0[j], 1e-20f); g1[j] = fmaxf(g1[j], 1e-20f); }
;                     if (n < 2) { f32x4 h0, h1; unpack_gate(*(const u32x4*)(mg + (size_t)row * 6144 + 2048 + col), h0, h1);
; #pragma unroll
;                         for (int j = 0; j < 4; ++j) { g0[j] *= __builtin_amdgcn_rcpf(fmaxf(h0[j], 1e-20f)); g1[j] *= __builtin_amdgcn_rcpf(fmaxf(h1[j], 1e-20f)); }
;                         acc[ai][bj][m][0] *= g0; acc[ai][bj][m][1] *= g1;
;                     } else {
;                         const f32x4 v0 = acc[ai][bj][m][0] * g0, v1 = acc[ai][bj][m][1] * g1;
;                         u32x4 w; w.x = pk2(v0[0], v0[1]); w.y = pk2(v0[2], v0[3]); w.z = pk2(v1[0], v1[1]); w.w = pk2(v1[2], v1[3]); *(u32x4*)(mrg + (size_t)row * 2048 + col) = w; } } }
	v_add_u32_e32 v3, 524288, v2
	v_lshlrev_b32_e32 v242, 16, v144
	v_and_b32_e32 v144, 0xffff0000, v144
	v_max_f32_e32 v242, 0x1e3ce508, v242
	v_max_f32_e32 v144, 0x1e3ce508, v144
	v_mul_f32_e32 v242, v64, v242
	v_mul_f32_e32 v144, v65, v144
	v_cvt_pk_bf16_f32 v178, v242, v144
	v_lshlrev_b32_e32 v242, 16, v145
	v_and_b32_e32 v145, 0xffff0000, v145
	v_max_f32_e32 v242, 0x1e3ce508, v242
	v_max_f32_e32 v145, 0x1e3ce508, v145
	v_mul_f32_e32 v242, v66, v242
	v_mul_f32_e32 v145, v67, v145
	v_cvt_pk_bf16_f32 v179, v242, v145
	v_lshlrev_b32_e32 v242, 16, v146
	v_and_b32_e32 v146, 0xffff0000, v146
	v_max_f32_e32 v242, 0x1e3ce508, v242
	v_max_f32_e32 v146, 0x1e3ce508, v146
	v_mul_f32_e32 v242, v60, v242
	v_mul_f32_e32 v146, v61, v146
	v_cvt_pk_bf16_f32 v180, v242, v146
	v_lshlrev_b32_e32 v242, 16, v147
	v_and_b32_e32 v147, 0xffff0000, v147
	v_max_f32_e32 v242, 0x1e3ce508, v242
	v_max_f32_e32 v147, 0x1e3ce508, v147
	v_mul_f32_e32 v242, v62, v242
	v_mul_f32_e32 v147, v63, v147
	v_cvt_pk_bf16_f32 v181, v242, v147
	global_store_dwordx4 v3, v[178:181], s[6:7] offset:0
	v_lshlrev_b32_e32 v242, 16, v148
	v_and_b32_e32 v148, 0xffff0000, v148
	v_max_f32_e32 v242, 0x1e3ce508, v242
	v_max_f32_e32 v148, 0x1e3ce508, v148
	v_mul_f32_e32 v242, v32, v242
	v_mul_f32_e32 v148, v33, v148
	v_cvt_pk_bf16_f32 v182, v242, v148
	v_lshlrev_b32_e32 v242, 16, v149
	v_and_b32_e32 v149, 0xffff0000, v149
	v_max_f32_e32 v242, 0x1e3ce508, v242
	v_max_f32_e32 v149, 0x1e3ce508, v149
	v_mul_f32_e32 v242, v34, v242
	v_mul_f32_e32 v149, v35, v149
	v_cvt_pk_bf16_f32 v183, v242, v149
	v_lshlrev_b32_e32 v242, 16, v150
	v_and_b32_e32 v150, 0xffff0000, v150
	v_max_f32_e32 v242, 0x1e3ce508, v242
	v_max_f32_e32 v150, 0x1e3ce508, v150
	v_mul_f32_e32 v242, v28, v242
	v_mul_f32_e32 v150, v29, v150
	v_cvt_pk_bf16_f32 v184, v242, v150
	v_lshlrev_b32_e32 v242, 16, v151
	v_and_b32_e32 v151, 0xffff0000, v151
	v_max_f32_e32 v242, 0x1e3ce508, v242
	v_max_f32_e32 v151, 0x1e3ce508, v151
	v_mul_f32_e32 v242, v30, v242
	v_mul_f32_e32 v151, v31, v151
	v_cvt_pk_bf16_f32 v185, v242, v151
	global_store_dwordx4 v3, v[182:185], s[6:7] offset:256
	v_add_u32_e32 v3, 589824, v2
	v_lshlrev_b32_e32 v242, 16, v152
	v_and_b32_e32 v152, 0xffff0000, v152
	v_max_f32_e32 v242, 0x1e3ce508, v242
	v_max_f32_e32 v152, 0x1e3ce508, v152
	v_mul_f32_e32 v242, v56, v242
	v_mul_f32_e32 v152, v57, v152
	v_cvt_pk_bf16_f32 v186, v242, v152
	v_lshlrev_b32_e32 v242, 16, v153
	v_and_b32_e32 v153, 0xffff0000, v153
	v_max_f32_e32 v242, 0x1e3ce508, v242
	v_max_f32_e32 v153, 0x1e3ce508, v153
	v_mul_f32_e32 v242, v58, v242
	v_mul_f32_e32 v153, v59, v153
	v_cvt_pk_bf16_f32 v187, v242, v153
	v_lshlrev_b32_e32 v242, 16, v154
	v_and_b32_e32 v154, 0xffff0000, v154
	v_max_f32_e32 v242, 0x1e3ce508, v242
	v_max_f32_e32 v154, 0x1e3ce508, v154
	v_mul_f32_e32 v242, v52, v242
	v_mul_f32_e32 v154, v53, v154
	v_cvt_pk_bf16_f32 v188, v242, v154
	v_lshlrev_b32_e32 v242, 16, v155
	v_and_b32_e32 v155, 0xffff0000, v155
	v_max_f32_e32 v242, 0x1e3ce508, v242
	v_max_f32_e32 v155, 0x1e3ce508, v155
	v_mul_f32_e32 v242, v54, v242
	v_mul_f32_e32 v155, v55, v155
	v_cvt_pk_bf16_f32 v189, v242, v155
	global_store_dwordx4 v3, v[186:189], s[6:7] offset:0
	v_lshlrev_b32_e32 v242, 16, v156
	v_and_b32_e32 v156, 0xffff0000, v156
	v_max_f32_e32 v242, 0x1e3ce508, v242
	v_max_f32_e32 v156, 0x1e3ce508, v156
	v_mul_f32_e32 v242, v24, v242
	v_mul_f32_e32 v156, v25, v156
	v_cvt_pk_bf16_f32 v190, v242, v156
	v_lshlrev_b32_e32 v242, 16, v157
	v_and_b32_e32 v157, 0xffff0000, v157
	v_max_f32_e32 v242, 0x1e3ce508, v242
	v_max_f32_e32 v157, 0x1e3ce508, v157
	v_mul_f32_e32 v242, v26, v242
	v_mul_f32_e32 v157, v27, v157
	v_cvt_pk_bf16_f32 v191, v242, v157
	v_lshlrev_b32_e32 v242, 16, v158
	v_and_b32_e32 v158, 0xffff0000, v158
	v_max_f32_e32 v242, 0x1e3ce508, v242
	v_max_f32_e32 v158, 0x1e3ce508, v158
	v_mul_f32_e32 v242, v20, v242
	v_mul_f32_e32 v158, v21, v158
	v_cvt_pk_bf16_f32 v192, v242, v158
	v_lshlrev_b32_e32 v242, 16, v159
	v_and_b32_e32 v159, 0xffff0000, v159
	v_max_f32_e32 v242, 0x1e3ce508, v242
	v_max_f32_e32 v159, 0x1e3ce508, v159
	v_mul_f32_e32 v242, v22, v242
	v_mul_f32_e32 v159, v23, v159
	v_cvt_pk_bf16_f32 v193, v242, v159
	global_store_dwordx4 v3, v[190:193], s[6:7] offset:256
	v_add_u32_e32 v3, 1966080, v0
	global_load_dwordx4 v[144:147], v3, s[22:23] offset:0
	global_load_dwordx4 v[148:151], v3, s[22:23] offset:256
	v_add_u32_e32 v3, 2162688, v0
	global_load_dwordx4 v[152:155], v3, s[22:23] offset:0
	global_load_dwordx4 v[156:159], v3, s[22:23] offset:256
	s_waitcnt vmcnt(0)
; __device__ __forceinline__ unsigned pk2(float lo, float hi) { f32x2 v = {lo, hi}; bf16x2_t b = __builtin_convertvector(v, bf16x2_t); return __builtin_bit_cast(unsigned, b); }
;     __device__ __forceinline__ bool keep_acc(const pg8::Unit& u) const { return (u.pm >> 5) < 2; }
; template <class Epi, class Sched, bool ALIGN_EPI = false, bool SP2 = false>
; __device__ __forceinline__ void gemm_phase(PG8_LAS unsigned char* lds, const Gemm g, const Sched& S, const Epi& E) {
;     ...
;         if (!E.keep_acc(cur)) {
; #pragma unroll
;         for (int a = 0; a < 2; ++a)
; #pragma unroll
;             for (int b = 0; b < 2; ++b)
; #pragma unroll
;                 for (int m = 0; m < 4; ++m)
; #pragma unroll
;                     for (int n = 0; n < 2; ++n) acc[a][b][m][n] = (f32x4){0.f, 0.f, 0.f, 0.f};
;     __device__ __forceinline__ void operator()(AccMut acc, const pg8::Unit& u, int wr, int wc, int fr, int fq) const {
;     ...
;                 for (int bj = 0; bj < 2; ++bj) { const int col = col0 + bj * 128;
;                     f32x4 g0, g1; unpack_gate(*(const u32x4*)(mg + (size_t)row * 6144 + col), g0, g1);
; #pragma unroll
;                     for (int j = 0; j < 4; ++j) { g0[j] = fmaxf(g0[j], 1e-20f); g1[j] = fmaxf(g1[j], 1e-20f); }
;                     if (n < 2) { f32x4 h0, h1; unpack_gate(*(const u32x4*)(mg + (size_t)row * 6144 + 2048 + col), h0, h1);
; #pragma unroll
;                         for (int j = 0; j < 4; ++j) { g0[j] *= __builtin_amdgcn_rcpf(fmaxf(h0[j], 1e-20f)); g1[j] *= __builtin_amdgcn_rcpf(fmaxf(h1[j], 1e-20f)); }
;                         acc[ai][bj][m][0] *= g0; acc[ai][bj][m][1] *= g1;
;                     } else {
;                         const f32x4 v0 = acc[ai][bj][m][0] * g0, v1 = acc[ai][bj][m][1] * g1;
;                         u32x4 w; w.x = pk2(v0[0], v0[1]); w.y = pk2(v0[2], v0[3]); w.z = pk2(v1[0], v1[1]); w.w = pk2(v1[2], v1[3]); *(u32x4*)(mrg + (size_t)row * 2048 + col) = w; } } }
	v_add_u32_e32 v3, 655360, v2
	v_lshlrev_b32_e32 v242, 16, v144
	v_and_b32_e32 v144, 0xffff0000, v144
	v_max_f32_e32 v242, 0x1e3ce508, v242
	v_max_f32_e32 v144, 0x1e3ce508, v144
	v_mul_f32_e32 v242, v48, v242
	v_mul_f32_e32 v144, v49, v144
	v_cvt_pk_bf16_f32 v194, v242, v144
	v_lshlrev_b32_e32 v242, 16, v145
	v_and_b32_e32 v145, 0xffff0000, v145
	v_max_f32_e32 v242, 0x1e3ce508, v242
	v_max_f32_e32 v145, 0x1e3ce508, v145
	v_mul_f32_e32 v242, v50, v242
	v_mul_f32_e32 v145, v51, v145
	v_cvt_pk_bf16_f32 v195, v242, v145
	v_lshlrev_b32_e32 v242, 16, v146
	v_and_b32_e32 v146, 0xffff0000, v146
	v_max_f32_e32 v242, 0x1e3ce508, v242
	v_max_f32_e32 v146, 0x1e3ce508, v146
	v_mul_f32_e32 v242, v44, v242
	v_mul_f32_e32 v146, v45, v146
	v_cvt_pk_bf16_f32 v196, v242, v146
	v_lshlrev_b32_e32 v242, 16, v147
	v_and_b32_e32 v147, 0xffff0000, v147
	v_max_f32_e32 v242, 0x1e3ce508, v242
	v_max_f32_e32 v147, 0x1e3ce508, v147
	v_mul_f32_e32 v242, v46, v242
	v_mul_f32_e32 v147, v47, v147
	v_cvt_pk_bf16_f32 v197, v242, v147
	global_store_dwordx4 v3, v[194:197], s[6:7] offset:0
	v_lshlrev_b32_e32 v242, 16, v148
	v_and_b32_e32 v148, 0xffff0000, v148
	v_max_f32_e32 v242, 0x1e3ce508, v242
	v_max_f32_e32 v148, 0x1e3ce508, v148
	v_mul_f32_e32 v242, v16, v242
	v_mul_f32_e32 v148, v17, v148
	v_cvt_pk_bf16_f32 v198, v242, v148
	v_lshlrev_b32_e32 v242, 16, v149
	v_and_b32_e32 v149, 0xffff0000, v149
	v_max_f32_e32 v242, 0x1e3ce508, v242
	v_max_f32_e32 v149, 0x1e3ce508, v149
	v_mul_f32_e32 v242, v18, v242
	v_mul_f32_e32 v149, v19, v149
	v_cvt_pk_bf16_f32 v199, v242, v149
	v_lshlrev_b32_e32 v242, 16, v150
	v_and_b32_e32 v150, 0xffff0000, v150
	v_max_f32_e32 v242, 0x1e3ce508, v242
	v_max_f32_e32 v150, 0x1e3ce508, v150
	v_mul_f32_e32 v242, v12, v242
	v_mul_f32_e32 v150, v13, v150
	v_cvt_pk_bf16_f32 v200, v242, v150
	v_lshlrev_b32_e32 v242, 16, v151
	v_and_b32_e32 v151, 0xffff0000, v151
	v_max_f32_e32 v242, 0x1e3ce508, v242
	v_max_f32_e32 v151, 0x1e3ce508, v151
	v_mul_f32_e32 v242, v14, v242
	v_mul_f32_e32 v151, v15, v151
	v_cvt_pk_bf16_f32 v201, v242, v151
	global_store_dwordx4 v3, v[198:201], s[6:7] offset:256
	v_add_u32_e32 v3, 720896, v2
	v_lshlrev_b32_e32 v242, 16, v152
	v_and_b32_e32 v152, 0xffff0000, v152
	v_max_f32_e32 v242, 0x1e3ce508, v242
	v_max_f32_e32 v152, 0x1e3ce508, v152
	v_mul_f32_e32 v242, v40, v242
	v_mul_f32_e32 v152, v41, v152
	v_cvt_pk_bf16_f32 v202, v242, v152
	v_lshlrev_b32_e32 v242, 16, v153
	v_and_b32_e32 v153, 0xffff0000, v153
	v_max_f32_e32 v242, 0x1e3ce508, v242
	v_max_f32_e32 v153, 0x1e3ce508, v153
	v_mul_f32_e32 v242, v42, v242
	v_mul_f32_e32 v153, v43, v153
	v_cvt_pk_bf16_f32 v203, v242, v153
	v_lshlrev_b32_e32 v242, 16, v154
	v_and_b32_e32 v154, 0xffff0000, v154
	v_max_f32_e32 v242, 0x1e3ce508, v242
	v_max_f32_e32 v154, 0x1e3ce508, v154
	v_mul_f32_e32 v242, v36, v242
	v_mul_f32_e32 v154, v37, v154
	v_cvt_pk_bf16_f32 v204, v242, v154
	v_lshlrev_b32_e32 v242, 16, v155
	v_and_b32_e32 v155, 0xffff0000, v155
	v_max_f32_e32 v242, 0x1e3ce508, v242
	v_max_f32_e32 v155, 0x1e3ce508, v155
	v_mul_f32_e32 v242, v38, v242
	v_mul_f32_e32 v155, v39, v155
	v_cvt_pk_bf16_f32 v205, v242, v155
	global_store_dwordx4 v3, v[202:205], s[6:7] offset:0
	v_lshlrev_b32_e32 v242, 16, v156
	v_and_b32_e32 v156, 0xffff0000, v156
	v_max_f32_e32 v242, 0x1e3ce508, v242
	v_max_f32_e32 v156, 0x1e3ce508, v156
	v_mul_f32_e32 v242, v8, v242
	v_mul_f32_e32 v156, v9, v156
	v_cvt_pk_bf16_f32 v224, v242, v156
	v_lshlrev_b32_e32 v242, 16, v157
	v_and_b32_e32 v157, 0xffff0000, v157
	v_max_f32_e32 v242, 0x1e3ce508, v242
	v_max_f32_e32 v157, 0x1e3ce508, v157
	v_mul_f32_e32 v242, v10, v242
	v_mul_f32_e32 v157, v11, v157
	v_cvt_pk_bf16_f32 v225, v242, v157
	v_lshlrev_b32_e32 v242, 16, v158
	v_and_b32_e32 v158, 0xffff0000, v158
	v_max_f32_e32 v242, 0x1e3ce508, v242
	v_max_f32_e32 v158, 0x1e3ce508, v158
	v_mul_f32_e32 v242, v4, v242
	v_mul_f32_e32 v158, v5, v158
	v_cvt_pk_bf16_f32 v226, v242, v158
	v_lshlrev_b32_e32 v242, 16, v159
	v_and_b32_e32 v159, 0xffff0000, v159
	v_max_f32_e32 v242, 0x1e3ce508, v242
	v_max_f32_e32 v159, 0x1e3ce508, v159
	v_mul_f32_e32 v242, v6, v242
	v_mul_f32_e32 v159, v7, v159
	v_cvt_pk_bf16_f32 v227, v242, v159
	global_store_dwordx4 v3, v[224:227], s[6:7] offset:256
.Lep3_done:
	s_andn2_b64 vcc, exec, s[38:39]
	s_mov_b64 s[12:13], -1
	s_cbranch_vccnz .LBB0_1231
.LBB0_1307:
	s_cmp_lt_i32 s2, 64
	s_cbranch_scc1 .LBB0_1309
	v_mov_b32_e32 v2, v1
	v_mov_b32_e32 v3, v1
	v_mov_b32_e32 v0, v1
	v_mov_b64_e32 v[6:7], v[2:3]
	v_mov_b64_e32 v[10:11], v[2:3]
	v_mov_b64_e32 v[14:15], v[2:3]
	v_mov_b64_e32 v[18:19], v[2:3]
	v_mov_b64_e32 v[22:23], v[2:3]
	v_mov_b64_e32 v[26:27], v[2:3]
	v_mov_b64_e32 v[30:31], v[2:3]
	v_mov_b64_e32 v[34:35], v[2:3]
	v_mov_b64_e32 v[38:39], v[2:3]
	v_mov_b64_e32 v[42:43], v[2:3]
	v_mov_b64_e32 v[46:47], v[2:3]
	v_mov_b64_e32 v[50:51], v[2:3]
	v_mov_b64_e32 v[54:55], v[2:3]
	v_mov_b64_e32 v[58:59], v[2:3]
	v_mov_b64_e32 v[62:63], v[2:3]
	v_mov_b64_e32 v[66:67], v[2:3]
	v_mov_b64_e32 v[70:71], v[2:3]
	v_mov_b64_e32 v[74:75], v[2:3]
	v_mov_b64_e32 v[78:79], v[2:3]
	v_mov_b64_e32 v[82:83], v[2:3]
	v_mov_b64_e32 v[86:87], v[2:3]
	v_mov_b64_e32 v[90:91], v[2:3]
	v_mov_b64_e32 v[94:95], v[2:3]
	v_mov_b64_e32 v[98:99], v[2:3]
	v_mov_b64_e32 v[102:103], v[2:3]
	v_mov_b64_e32 v[106:107], v[2:3]
	v_mov_b64_e32 v[110:111], v[2:3]
	v_mov_b64_e32 v[114:115], v[2:3]
	v_mov_b64_e32 v[118:119], v[2:3]
	v_mov_b64_e32 v[122:123], v[2:3]
	v_mov_b64_e32 v[126:127], v[2:3]
	v_mov_b64_e32 v[130:131], v[2:3]
	v_mov_b64_e32 v[4:5], v[0:1]
	v_mov_b64_e32 v[8:9], v[0:1]
	v_mov_b64_e32 v[12:13], v[0:1]
	v_mov_b64_e32 v[16:17], v[0:1]
	v_mov_b64_e32 v[20:21], v[0:1]
	v_mov_b64_e32 v[24:25], v[0:1]
	v_mov_b64_e32 v[28:29], v[0:1]
	v_mov_b64_e32 v[32:33], v[0:1]
	v_mov_b64_e32 v[36:37], v[0:1]
	v_mov_b64_e32 v[40:41], v[0:1]
	v_mov_b64_e32 v[44:45], v[0:1]
	v_mov_b64_e32 v[48:49], v[0:1]
	v_mov_b64_e32 v[52:53], v[0:1]
	v_mov_b64_e32 v[56:57], v[0:1]
	v_mov_b64_e32 v[60:61], v[0:1]
	v_mov_b64_e32 v[64:65], v[0:1]
	v_mov_b64_e32 v[68:69], v[0:1]
	v_mov_b64_e32 v[72:73], v[0:1]
	v_mov_b64_e32 v[76:77], v[0:1]
	v_mov_b64_e32 v[80:81], v[0:1]
	v_mov_b64_e32 v[84:85], v[0:1]
	v_mov_b64_e32 v[88:89], v[0:1]
	v_mov_b64_e32 v[92:93], v[0:1]
	v_mov_b64_e32 v[96:97], v[0:1]
	v_mov_b64_e32 v[100:101], v[0:1]
	v_mov_b64_e32 v[104:105], v[0:1]
	v_mov_b64_e32 v[108:109], v[0:1]
	v_mov_b64_e32 v[112:113], v[0:1]
	v_mov_b64_e32 v[116:117], v[0:1]
	v_mov_b64_e32 v[120:121], v[0:1]
	v_mov_b64_e32 v[124:125], v[0:1]
	v_mov_b64_e32 v[128:129], v[0:1]

; __device__ __forceinline__ void phase_ln(const Params& P, int l) {
;     ...
;     const float* g = P.ln_g + (size_t)(l > 0 ? l - 1 : 0) * 2048; const float* bb = P.ln_b + (size_t)(l > 0 ? l - 1 : 0) * 2048;
;     const float* mod = (const float*)(P.ws + WS_MOD) + (size_t)(l < 4 ? l : 0) * 4 * 6144;
;     const float* gate = (const float*)(P.ws + WS_MOD) + (size_t)(l > 0 ? l - 1 : 0) * 4 * 6144 + 4096;
;     for (int row = bx * 8 + wid; row < T; row += G * 8) {
;         f32x4 v[8];
; #pragma unroll
;         for (int i = 0; i < 8; ++i) v[i] = *(const f32x4*)(xsrc + (size_t)row * 2048 + (i * 64 + lane) * 4);
;         if (l >= 1) {
;             const float* gp = gate + (size_t)(row >> 11) * 6144;
; #pragma unroll
;             for (int i = 0; i < 8; ++i) { const int col = (i * 64 + lane) * 4; const u32x2 ow = *(const u32x2*)(outb + (size_t)row * 2048 + col); const f32x4 gv = *(const f32x4*)(gp + col);
;                 f32x4 o; o[0] = __uint_as_float(ow.x << 16); o[1] = __uint_as_float(ow.x & 0xffff0000u); o[2] = __uint_as_float(ow.y << 16); o[3] = __uint_as_float(ow.y & 0xffff0000u);
;                 v[i] = v[i] * ALPHA + gv * o; }
;         }
;         float mean, rstd; row_stats(v, mean, rstd);
;         if (l >= 1) {
;             float* dst = (l == 4) ? P.out : X;
; #pragma unroll
;             for (int i = 0; i < 8; ++i) { const int col = (i * 64 + lane) * 4; const f32x4 gv = *(const f32x4*)(g + col), bv = *(const f32x4*)(bb + col);
;                 v[i] = (v[i] - mean) * rstd * gv + bv; *(f32x4*)(dst + (size_t)row * 2048 + col) = v[i]; }
.LBB0_1439:
	s_cmp_lt_i32 s90, 26
	s_cselect_b64 s[0:1], -1, 0
	s_cmp_gt_i32 s91, 25
	s_cselect_b64 s[2:3], -1, 0
	s_and_b64 s[0:1], s[0:1], s[2:3]
	s_and_b64 vcc, exec, s[0:1]
	s_cbranch_vccz .LBB0_1443
	s_load_dwordx4 s[8:11], s[92:93], 0x68
	s_load_dwordx2 s[4:5], s[92:93], 0x78
	s_load_dword s12, s[92:93], 0x90
	v_readlane_b32 s13, v253, 0
	v_readfirstlane_b32 s14, v208
	v_and_b32_e32 v3, 63, v208
	v_lshlrev_b32_e32 v0, 4, v3
	v_add_u32_e32 v2, 0x1000, v0
	v_xor_b32_e32 v4, 32, v3
	v_lshlrev_b32_e32 v4, 2, v4
	v_xor_b32_e32 v5, 16, v3
	v_lshlrev_b32_e32 v5, 2, v5
	v_xor_b32_e32 v6, 8, v3
	v_lshlrev_b32_e32 v6, 2, v6
	v_xor_b32_e32 v7, 4, v3
	v_lshlrev_b32_e32 v7, 2, v7
	v_xor_b32_e32 v8, 2, v3
	v_lshlrev_b32_e32 v8, 2, v8
	v_xor_b32_e32 v9, 1, v3
	v_lshlrev_b32_e32 v9, 2, v9
	v_lshlrev_b32_e32 v3, 3, v3
	s_lshr_b32 s14, s14, 6
	s_lshl_b32 s13, s13, 3
	s_add_i32 s13, s13, s14
	s_mov_b32 s17, 0x3fd744fd
	s_waitcnt lgkmcnt(0)
	s_lshl_b32 s12, s12, 3
	s_cmp_ge_u32 s13, 0x2000
	s_cbranch_scc1 .Llnf_done
	s_add_u32 s8, s8, 0x6000
	s_addc_u32 s9, s9, 0
	s_add_u32 s10, s10, 0x6000
	s_addc_u32 s11, s11, 0
	global_load_dwordx4 v[48:51], v0, s[8:9] offset:0
	global_load_dwordx4 v[52:55], v0, s[8:9] offset:1024
	global_load_dwordx4 v[56:59], v0, s[8:9] offset:2048
	global_load_dwordx4 v[60:63], v0, s[8:9] offset:3072
	global_load_dwordx4 v[64:67], v2, s[8:9] offset:0
	global_load_dwordx4 v[68:71], v2, s[8:9] offset:1024
	global_load_dwordx4 v[72:75], v2, s[8:9] offset:2048
	global_load_dwordx4 v[76:79], v2, s[8:9] offset:3072
	global_load_dwordx4 v[80:83], v0, s[10:11] offset:0
	global_load_dwordx4 v[84:87], v0, s[10:11] offset:1024
	global_load_dwordx4 v[88:91], v0, s[10:11] offset:2048
	global_load_dwordx4 v[92:95], v0, s[10:11] offset:3072
	global_load_dwordx4 v[96:99], v2, s[10:11] offset:0
	global_load_dwordx4 v[100:103], v2, s[10:11] offset:1024
	global_load_dwordx4 v[104:107], v2, s[10:11] offset:2048
	global_load_dwordx4 v[108:111], v2, s[10:11] offset:3072
.Llnf_row:
	s_lshl_b32 s10, s13, 13
	s_add_u32 s10, s10, 0x17c64100
	s_add_u32 s22, s88, s10
	s_addc_u32 s23, s89, 0
	global_load_dwordx4 v[16:19], v0, s[22:23] offset:0
	global_load_dwordx4 v[20:23], v0, s[22:23] offset:1024
	global_load_dwordx4 v[24:27], v0, s[22:23] offset:2048
	global_load_dwordx4 v[28:31], v0, s[22:23] offset:3072
	global_load_dwordx4 v[32:35], v2, s[22:23] offset:0
	global_load_dwordx4 v[36:39], v2, s[22:23] offset:1024
	global_load_dwordx4 v[40:43], v2, s[22:23] offset:2048
	global_load_dwordx4 v[44:47], v2, s[22:23] offset:3072
	s_lshl_b32 s11, s13, 12
	s_add_u32 s11, s11, 0x1bc64100
	s_add_u32 s24, s88, s11
	s_addc_u32 s25, s89, 0
	global_load_dwordx2 v[144:145], v3, s[24:25] offset:0
	global_load_dwordx2 v[146:147], v3, s[24:25] offset:512
	global_load_dwordx2 v[148:149], v3, s[24:25] offset:1024
	global_load_dwordx2 v[150:151], v3, s[24:25] offset:1536
	global_load_dwordx2 v[152:153], v3, s[24:25] offset:2048
	global_load_dwordx2 v[154:155], v3, s[24:25] offset:2560
	global_load_dwordx2 v[156:157], v3, s[24:25] offset:3072
	global_load_dwordx2 v[158:159], v3, s[24:25] offset:3584
	s_lshr_b32 s11, s13, 11
	s_mul_i32 s11, s11, 0x6000
	s_add_u32 s11, s11, 0x15a50100
	s_add_u32 s26, s88, s11
	s_addc_u32 s27, s89, 0
	global_load_dwordx4 v[112:115], v0, s[26:27] offset:0
	global_load_dwordx4 v[116:119], v0, s[26:27] offset:1024
	global_load_dwordx4 v[120:123], v0, s[26:27] offset:2048
	global_load_dwordx4 v[124:127], v0, s[26:27] offset:3072
	global_load_dwordx4 v[128:131], v2, s[26:27] offset:0
	global_load_dwordx4 v[132:135], v2, s[26:27] offset:1024
	global_load_dwordx4 v[136:139], v2, s[26:27] offset:2048
	global_load_dwordx4 v[140:143], v2, s[26:27] offset:3072
	s_waitcnt vmcnt(0)
	v_lshlrev_b32_e32 v224, 16, v144
	v_and_b32_e32 v225, 0xffff0000, v144
	v_lshlrev_b32_e32 v226, 16, v145
	v_and_b32_e32 v227, 0xffff0000, v145
	v_pk_mul_f32 v[224:225], v[112:113], v[224:225]
	v_pk_mul_f32 v[226:227], v[114:115], v[226:227]
	v_fma_f32 v16, v16, s17, v224
	v_fma_f32 v17, v17, s17, v225
	v_fma_f32 v18, v18, s17, v226
	v_fma_f32 v19, v19, s17, v227
	v_lshlrev_b32_e32 v224, 16, v146
	v_and_b32_e32 v225, 0xffff0000, v146
	v_lshlrev_b32_e32 v226, 16, v147
	v_and_b32_e32 v227, 0xffff0000, v147
	v_pk_mul_f32 v[224:225], v[116:117], v[224:225]
	v_pk_mul_f32 v[226:227], v[118:119], v[226:227]
	v_fma_f32 v20, v20, s17, v224
	v_fma_f32 v21, v21, s17, v225
	v_fma_f32 v22, v22, s17, v226
	v_fma_f32 v23, v23, s17, v227
	v_lshlrev_b32_e32 v224, 16, v148
	v_and_b32_e32 v225, 0xffff0000, v148
	v_lshlrev_b32_e32 v226, 16, v149
	v_and_b32_e32 v227, 0xffff0000, v149
	v_pk_mul_f32 v[224:225], v[120:121], v[224:225]
	v_pk_mul_f32 v[226:227], v[122:123], v[226:227]
	v_fma_f32 v24, v24, s17, v224
	v_fma_f32 v25, v25, s17, v225
	v_fma_f32 v26, v26, s17, v226
	v_fma_f32 v27, v27, s17, v227
	v_lshlrev_b32_e32 v224, 16, v150
	v_and_b32_e32 v225, 0xffff0000, v150
	v_lshlrev_b32_e32 v226, 16, v151
	v_and_b32_e32 v227, 0xffff0000, v151
	v_pk_mul_f32 v[224:225], v[124:125], v[224:225]
	v_pk_mul_f32 v[226:227], v[126:127], v[226:227]
	v_fma_f32 v28, v28, s17, v224
	v_fma_f32 v29, v29, s17, v225
	v_fma_f32 v30, v30, s17, v226
	v_fma_f32 v31, v31, s17, v227
	v_lshlrev_b32_e32 v224, 16, v152
	v_and_b32_e32 v225, 0xffff0000, v152
	v_lshlrev_b32_e32 v226, 16, v153
	v_and_b32_e32 v227, 0xffff0000, v153
	v_pk_mul_f32 v[224:225], v[128:129], v[224:225]
	v_pk_mul_f32 v[226:227], v[130:131], v[226:227]
	v_fma_f32 v32, v32, s17, v224
	v_fma_f32 v33, v33, s17, v225
	v_fma_f32 v34, v34, s17, v226
	v_fma_f32 v35, v35, s17, v227
	v_lshlrev_b32_e32 v224, 16, v154
	v_and_b32_e32 v225, 0xffff0000, v154
; __device__ __forceinline__ void row_stats(const f32x4 (&v)[8], float& mean, float& rstd) {
;     float s = 0.f;
; #pragma unroll
;     for (int i = 0; i < 8; ++i) s += (v[i][0] + v[i][1]) + (v[i][2] + v[i][3]);
;     mean = wave_sum(s) * (1.f / 2048.f);
;     float q = 0.f;
; #pragma unroll
;     for (int i = 0; i < 8; ++i) { const f32x4 d = v[i] - mean; q += (d[0] * d[0] + d[1] * d[1]) + (d[2] * d[2] + d[3] * d[3]); }
;     rstd = rsqrtf(wave_sum(q) * (1.f / 2048.f) + 1e-5f);
; __device__ __forceinline__ void phase_ln(const Params& P, int l) {
;     ...
;             for (int i = 0; i < 8; ++i) { const int col = (i * 64 + lane) * 4; const u32x2 ow = *(const u32x2*)(outb + (size_t)row * 2048 + col); const f32x4 gv = *(const f32x4*)(gp + col);
;                 f32x4 o; o[0] = __uint_as_float(ow.x << 16); o[1] = __uint_as_float(ow.x & 0xffff0000u); o[2] = __uint_as_float(ow.y << 16); o[3] = __uint_as_float(ow.y & 0xffff0000u);
;                 v[i] = v[i] * ALPHA + gv * o; }
	v_lshlrev_b32_e32 v226, 16, v155
	v_and_b32_e32 v227, 0xffff0000, v155
	v_pk_mul_f32 v[224:225], v[132:133], v[224:225]
	v_pk_mul_f32 v[226:227], v[134:135], v[226:227]
	v_fma_f32 v36, v36, s17, v224
	v_fma_f32 v37, v37, s17, v225
	v_fma_f32 v38, v38, s17, v226
	v_fma_f32 v39, v39, s17, v227
	v_lshlrev_b32_e32 v224, 16, v156
	v_and_b32_e32 v225, 0xffff0000, v156
	v_lshlrev_b32_e32 v226, 16, v157
	v_and_b32_e32 v227, 0xffff0000, v157
	v_pk_mul_f32 v[224:225], v[136:137], v[224:225]
	v_pk_mul_f32 v[226:227], v[138:139], v[226:227]
	v_fma_f32 v40, v40, s17, v224
	v_fma_f32 v41, v41, s17, v225
	v_fma_f32 v42, v42, s17, v226
	v_fma_f32 v43, v43, s17, v227
	v_lshlrev_b32_e32 v224, 16, v158
	v_and_b32_e32 v225, 0xffff0000, v158
	v_lshlrev_b32_e32 v226, 16, v159
	v_and_b32_e32 v227, 0xffff0000, v159
	v_pk_mul_f32 v[224:225], v[140:141], v[224:225]
	v_pk_mul_f32 v[226:227], v[142:143], v[226:227]
	v_fma_f32 v44, v44, s17, v224
	v_fma_f32 v45, v45, s17, v225
	v_fma_f32 v46, v46, s17, v226
	v_fma_f32 v47, v47, s17, v227
	v_pk_add_f32 v[224:225], v[16:17], v[18:19]
	v_pk_add_f32 v[224:225], v[224:225], v[20:21]
	v_pk_add_f32 v[224:225], v[224:225], v[22:23]
	v_pk_add_f32 v[224:225], v[224:225], v[24:25]
	v_pk_add_f32 v[224:225], v[224:225], v[26:27]
	v_pk_add_f32 v[224:225], v[224:225], v[28:29]
	v_pk_add_f32 v[224:225], v[224:225], v[30:31]
	v_pk_add_f32 v[224:225], v[224:225], v[32:33]
	v_pk_add_f32 v[224:225], v[224:225], v[34:35]
	v_pk_add_f32 v[224:225], v[224:225], v[36:37]
	v_pk_add_f32 v[224:225], v[224:225], v[38:39]
	v_pk_add_f32 v[224:225], v[224:225], v[40:41]
	v_pk_add_f32 v[224:225], v[224:225], v[42:43]
	v_pk_add_f32 v[224:225], v[224:225], v[44:45]
	v_pk_add_f32 v[224:225], v[224:225], v[46:47]
	v_add_f32_e32 v12, v224, v225
	ds_bpermute_b32 v13, v4, v12
	s_waitcnt lgkmcnt(0)
	v_add_f32_e32 v12, v12, v13
	ds_bpermute_b32 v13, v5, v12
	s_waitcnt lgkmcnt(0)
	v_add_f32_e32 v12, v12, v13
	ds_bpermute_b32 v13, v6, v12
	s_waitcnt lgkmcnt(0)
	v_add_f32_e32 v12, v12, v13
	ds_bpermute_b32 v13, v7, v12
	s_waitcnt lgkmcnt(0)
	v_add_f32_e32 v12, v12, v13
	ds_bpermute_b32 v13, v8, v12
	s_waitcnt lgkmcnt(0)
	v_add_f32_e32 v12, v12, v13
	ds_bpermute_b32 v13, v9, v12
	s_waitcnt lgkmcnt(0)
	v_add_f32_e32 v12, v12, v13
	v_mul_f32_e32 v14, 0x3a000000, v12
	v_pk_add_f32 v[226:227], v[16:17], v[14:15] op_sel_hi:[1,0] neg_lo:[0,1] neg_hi:[0,1]
	v_pk_mul_f32 v[224:225], v[226:227], v[226:227]
	v_pk_add_f32 v[226:227], v[18:19], v[14:15] op_sel_hi:[1,0] neg_lo:[0,1] neg_hi:[0,1]
	v_pk_fma_f32 v[224:225], v[226:227], v[226:227], v[224:225]
	v_pk_add_f32 v[226:227], v[20:21], v[14:15] op_sel_hi:[1,0] neg_lo:[0,1] neg_hi:[0,1]
	v_pk_fma_f32 v[224:225], v[226:227], v[226:227], v[224:225]
	v_pk_add_f32 v[226:227], v[22:23], v[14:15] op_sel_hi:[1,0] neg_lo:[0,1] neg_hi:[0,1]
	v_pk_fma_f32 v[224:225], v[226:227], v[226:227], v[224:225]
	v_pk_add_f32 v[226:227], v[24:25], v[14:15] op_sel_hi:[1,0] neg_lo:[0,1] neg_hi:[0,1]
	v_pk_fma_f32 v[224:225], v[226:227], v[226:227], v[224:225]
	v_pk_add_f32 v[226:227], v[26:27], v[14:15] op_sel_hi:[1,0] neg_lo:[0,1] neg_hi:[0,1]
	v_pk_fma_f32 v[224:225], v[226:227], v[226:227], v[224:225]
	v_pk_add_f32 v[226:227], v[28:29], v[14:15] op_sel_hi:[1,0] neg_lo:[0,1] neg_hi:[0,1]
	v_pk_fma_f32 v[224:225], v[226:227], v[226:227], v[224:225]
	v_pk_add_f32 v[226:227], v[30:31], v[14:15] op_sel_hi:[1,0] neg_lo:[0,1] neg_hi:[0,1]
	v_pk_fma_f32 v[224:225], v[226:227], v[226:227], v[224:225]
	v_pk_add_f32 v[226:227], v[32:33], v[14:15] op_sel_hi:[1,0] neg_lo:[0,1] neg_hi:[0,1]
	v_pk_fma_f32 v[224:225], v[226:227], v[226:227], v[224:225]
	v_pk_add_f32 v[226:227], v[34:35], v[14:15] op_sel_hi:[1,0] neg_lo:[0,1] neg_hi:[0,1]
	v_pk_fma_f32 v[224:225], v[226:227], v[226:227], v[224:225]
	v_pk_add_f32 v[226:227], v[36:37], v[14:15] op_sel_hi:[1,0] neg_lo:[0,1] neg_hi:[0,1]
	v_pk_fma_f32 v[224:225], v[226:227], v[226:227], v[224:225]
	v_pk_add_f32 v[226:227], v[38:39], v[14:15] op_sel_hi:[1,0] neg_lo:[0,1] neg_hi:[0,1]
	v_pk_fma_f32 v[224:225], v[226:227], v[226:227], v[224:225]
	v_pk_add_f32 v[226:227], v[40:41], v[14:15] op_sel_hi:[1,0] neg_lo:[0,1] neg_hi:[0,1]
	v_pk_fma_f32 v[224:225], v[226:227], v[226:227], v[224:225]
	v_pk_add_f32 v[226:227], v[42:43], v[14:15] op_sel_hi:[1,0] neg_lo:[0,1] neg_hi:[0,1]
	v_pk_fma_f32 v[224:225], v[226:227], v[226:227], v[224:225]
	v_pk_add_f32 v[226:227], v[44:45], v[14:15] op_sel_hi:[1,0] neg_lo:[0,1] neg_hi:[0,1]
	v_pk_fma_f32 v[224:225], v[226:227], v[226:227], v[224:225]
	v_pk_add_f32 v[226:227], v[46:47], v[14:15] op_sel_hi:[1,0] neg_lo:[0,1] neg_hi:[0,1]
	v_pk_fma_f32 v[224:225], v[226:227], v[226:227], v[224:225]
	v_add_f32_e32 v12, v224, v225
	ds_bpermute_b32 v13, v4, v12
	s_waitcnt lgkmcnt(0)
; __device__ __forceinline__ int my_tid() { int t = threadIdx.x; asm volatile("" : "+v"(t)); return t; }
; __device__ __forceinline__ int my_bx() { int b = blockIdx.x; asm volatile("" : "+s"(b)); return b; }
; __device__ __forceinline__ void row_stats(const f32x4 (&v)[8], float& mean, float& rstd) {
;     ...
;     for (int i = 0; i < 8; ++i) { const f32x4 d = v[i] - mean; q += (d[0] * d[0] + d[1] * d[1]) + (d[2] * d[2] + d[3] * d[3]); }
;     rstd = rsqrtf(wave_sum(q) * (1.f / 2048.f) + 1e-5f);
; }
; __device__ __forceinline__ void phase_ln(const Params& P, int l) {
;     const int tid = my_tid(), bx = my_bx(), G = my_G();
;     const int wid = tid >> 6, lane = tid & 63;
;     float* X = (float*)(P.ws + WS_X); bf16_t* U = (bf16_t*)(P.ws + WS_U);
;     const float* xsrc = (l <= 1) ? P.x : X;
;     const bf16_t* outb = (const bf16_t*)(P.ws + WS_MRG2);
;     const float* g = P.ln_g + (size_t)(l > 0 ? l - 1 : 0) * 2048; const float* bb = P.ln_b + (size_t)(l > 0 ? l - 1 : 0) * 2048;
;     const float* mod = (const float*)(P.ws + WS_MOD) + (size_t)(l < 4 ? l : 0) * 4 * 6144;
;     const float* gate = (const float*)(P.ws + WS_MOD) + (size_t)(l > 0 ? l - 1 : 0) * 4 * 6144 + 4096;
;     for (int row = bx * 8 + wid; row < T; row += G * 8) {
;         f32x4 v[8];
; #pragma unroll
;         for (int i = 0; i < 8; ++i) v[i] = *(const f32x4*)(xsrc + (size_t)row * 2048 + (i * 64 + lane) * 4);
;         if (l >= 1) {
;             const float* gp = gate + (size_t)(row >> 11) * 6144;
; #pragma unroll
;             for (int i = 0; i < 8; ++i) { const int col = (i * 64 + lane) * 4; const u32x2 ow = *(const u32x2*)(outb + (size_t)row * 2048 + col); const f32x4 gv = *(const f32x4*)(gp + col);
;                 f32x4 o; o[0] = __uint_as_float(ow.x << 16); o[1] = __uint_as_float(ow.x & 0xffff0000u); o[2] = __uint_as_float(ow.y << 16); o[3] = __uint_as_float(ow.y & 0xffff0000u);
;                 v[i] = v[i] * ALPHA + gv * o; }
;         }
;         float mean, rstd; row_stats(v, mean, rstd);
;         if (l >= 1) {
;             float* dst = (l == 4) ? P.out : X;
; #pragma unroll
;             for (int i = 0; i < 8; ++i) { const int col = (i * 64 + lane) * 4; const f32x4 gv = *(const f32x4*)(g + col), bv = *(const f32x4*)(bb + col);
;                 v[i] = (v[i] - mean) * rstd * gv + bv; *(f32x4*)(dst + (size_t)row * 2048 + col) = v[i]; }
;             if (l == 4) continue;
	v_add_f32_e32 v12, v12, v13
	ds_bpermute_b32 v13, v5, v12
	s_waitcnt lgkmcnt(0)
	v_add_f32_e32 v12, v12, v13
	ds_bpermute_b32 v13, v6, v12
	s_waitcnt lgkmcnt(0)
	v_add_f32_e32 v12, v12, v13
	ds_bpermute_b32 v13, v7, v12
	s_waitcnt lgkmcnt(0)
	v_add_f32_e32 v12, v12, v13
	ds_bpermute_b32 v13, v8, v12
	s_waitcnt lgkmcnt(0)
	v_add_f32_e32 v12, v12, v13
	ds_bpermute_b32 v13, v9, v12
	s_waitcnt lgkmcnt(0)
	v_add_f32_e32 v12, v12, v13
	v_mul_f32_e32 v12, 0x3a000000, v12
	v_add_f32_e32 v12, 0x3727c5ac, v12
	v_rsq_f32_e32 v12, v12
	s_nop 0
	v_pk_add_f32 v[226:227], v[16:17], v[14:15] op_sel_hi:[1,0] neg_lo:[0,1] neg_hi:[0,1]
	v_pk_mul_f32 v[226:227], v[226:227], v[12:13] op_sel_hi:[1,0]
	v_pk_fma_f32 v[176:177], v[226:227], v[48:49], v[80:81]
	v_pk_add_f32 v[226:227], v[18:19], v[14:15] op_sel_hi:[1,0] neg_lo:[0,1] neg_hi:[0,1]
	v_pk_mul_f32 v[226:227], v[226:227], v[12:13] op_sel_hi:[1,0]
	v_pk_fma_f32 v[178:179], v[226:227], v[50:51], v[82:83]
	v_pk_add_f32 v[226:227], v[20:21], v[14:15] op_sel_hi:[1,0] neg_lo:[0,1] neg_hi:[0,1]
	v_pk_mul_f32 v[226:227], v[226:227], v[12:13] op_sel_hi:[1,0]
	v_pk_fma_f32 v[180:181], v[226:227], v[52:53], v[84:85]
	v_pk_add_f32 v[226:227], v[22:23], v[14:15] op_sel_hi:[1,0] neg_lo:[0,1] neg_hi:[0,1]
	v_pk_mul_f32 v[226:227], v[226:227], v[12:13] op_sel_hi:[1,0]
	v_pk_fma_f32 v[182:183], v[226:227], v[54:55], v[86:87]
	v_pk_add_f32 v[226:227], v[24:25], v[14:15] op_sel_hi:[1,0] neg_lo:[0,1] neg_hi:[0,1]
	v_pk_mul_f32 v[226:227], v[226:227], v[12:13] op_sel_hi:[1,0]
	v_pk_fma_f32 v[184:185], v[226:227], v[56:57], v[88:89]
	v_pk_add_f32 v[226:227], v[26:27], v[14:15] op_sel_hi:[1,0] neg_lo:[0,1] neg_hi:[0,1]
	v_pk_mul_f32 v[226:227], v[226:227], v[12:13] op_sel_hi:[1,0]
	v_pk_fma_f32 v[186:187], v[226:227], v[58:59], v[90:91]
	v_pk_add_f32 v[226:227], v[28:29], v[14:15] op_sel_hi:[1,0] neg_lo:[0,1] neg_hi:[0,1]
	v_pk_mul_f32 v[226:227], v[226:227], v[12:13] op_sel_hi:[1,0]
	v_pk_fma_f32 v[188:189], v[226:227], v[60:61], v[92:93]
	v_pk_add_f32 v[226:227], v[30:31], v[14:15] op_sel_hi:[1,0] neg_lo:[0,1] neg_hi:[0,1]
	v_pk_mul_f32 v[226:227], v[226:227], v[12:13] op_sel_hi:[1,0]
	v_pk_fma_f32 v[190:191], v[226:227], v[62:63], v[94:95]
	v_pk_add_f32 v[226:227], v[32:33], v[14:15] op_sel_hi:[1,0] neg_lo:[0,1] neg_hi:[0,1]
	v_pk_mul_f32 v[226:227], v[226:227], v[12:13] op_sel_hi:[1,0]
	v_pk_fma_f32 v[192:193], v[226:227], v[64:65], v[96:97]
	v_pk_add_f32 v[226:227], v[34:35], v[14:15] op_sel_hi:[1,0] neg_lo:[0,1] neg_hi:[0,1]
	v_pk_mul_f32 v[226:227], v[226:227], v[12:13] op_sel_hi:[1,0]
	v_pk_fma_f32 v[194:195], v[226:227], v[66:67], v[98:99]
	v_pk_add_f32 v[226:227], v[36:37], v[14:15] op_sel_hi:[1,0] neg_lo:[0,1] neg_hi:[0,1]
	v_pk_mul_f32 v[226:227], v[226:227], v[12:13] op_sel_hi:[1,0]
	v_pk_fma_f32 v[196:197], v[226:227], v[68:69], v[100:101]
	v_pk_add_f32 v[226:227], v[38:39], v[14:15] op_sel_hi:[1,0] neg_lo:[0,1] neg_hi:[0,1]
	v_pk_mul_f32 v[226:227], v[226:227], v[12:13] op_sel_hi:[1,0]
	v_pk_fma_f32 v[198:199], v[226:227], v[70:71], v[102:103]
	v_pk_add_f32 v[226:227], v[40:41], v[14:15] op_sel_hi:[1,0] neg_lo:[0,1] neg_hi:[0,1]
	v_pk_mul_f32 v[226:227], v[226:227], v[12:13] op_sel_hi:[1,0]
	v_pk_fma_f32 v[200:201], v[226:227], v[72:73], v[104:105]
	v_pk_add_f32 v[226:227], v[42:43], v[14:15] op_sel_hi:[1,0] neg_lo:[0,1] neg_hi:[0,1]
	v_pk_mul_f32 v[226:227], v[226:227], v[12:13] op_sel_hi:[1,0]
	v_pk_fma_f32 v[202:203], v[226:227], v[74:75], v[106:107]
	v_pk_add_f32 v[226:227], v[44:45], v[14:15] op_sel_hi:[1,0] neg_lo:[0,1] neg_hi:[0,1]
	v_pk_mul_f32 v[226:227], v[226:227], v[12:13] op_sel_hi:[1,0]
	v_pk_fma_f32 v[204:205], v[226:227], v[76:77], v[108:109]
	v_pk_add_f32 v[226:227], v[46:47], v[14:15] op_sel_hi:[1,0] neg_lo:[0,1] neg_hi:[0,1]
	v_pk_mul_f32 v[226:227], v[226:227], v[12:13] op_sel_hi:[1,0]
	v_pk_fma_f32 v[206:207], v[226:227], v[78:79], v[110:111]
	s_lshl_b32 s10, s13, 13
	s_add_u32 s6, s4, s10
	s_addc_u32 s7, s5, 0
	global_store_dwordx4 v0, v[176:179], s[6:7] offset:0
	global_store_dwordx4 v0, v[180:183], s[6:7] offset:1024
	global_store_dwordx4 v0, v[184:187], s[6:7] offset:2048
	global_store_dwordx4 v0, v[188:191], s[6:7] offset:3072
	global_store_dwordx4 v2, v[192:195], s[6:7] offset:0
	global_store_dwordx4 v2, v[196:199], s[6:7] offset:1024
	global_store_dwordx4 v2, v[200:203], s[6:7] offset:2048
	global_store_dwordx4 v2, v[204:207], s[6:7] offset:3072
	s_add_i32 s13, s13, s12
	s_cmp_lt_u32 s13, 0x2000
	s_cbranch_scc1 .Llnf_row
.Llnf_done:
.LBB0_1443:
	s_endpgm
